# next unit's K-tile-1 A-operand LDS-DMA loads issued at the previous unit's K-loop exit (in front of the epilogue) instead of in the peeled first iteration, so their cold-miss latency hides behind the
# speedup vs baseline: 1.0013x; 1.0013x over previous
.LBB0_132:
	s_ashr_i32 s25, s24, 31
	s_lshl_b64 s[28:29], s[24:25], 20
	v_readlane_b32 s25, v254, 62
	s_add_u32 s28, s25, s28
	v_readlane_b32 s25, v254, 63
	s_addc_u32 s29, s25, s29
	s_and_b64 s[4:5], s[4:5], exec
	s_cselect_b32 s25, s29, s31
	s_cselect_b32 s37, s28, s30
	s_add_u32 s50, s30, 0x100
	s_addc_u32 s51, s31, 0
	s_mov_b32 s57, -2
	ds_read_b128 v[130:133], v224
	ds_read_b128 v[134:137], v224 offset:1024
	ds_read_b128 v[138:141], v224 offset:2048
	ds_read_b128 v[142:145], v224 offset:3072
	ds_read_b128 v[146:149], v224 offset:16384
	ds_read_b128 v[162:165], v224 offset:17408
	ds_read_b128 v[166:169], v224 offset:18432
	ds_read_b128 v[170:173], v224 offset:19456
	ds_read_b128 v[174:177], v225
	ds_read_b128 v[178:181], v225 offset:1024
	ds_read_b128 v[182:185], v225 offset:2048
	ds_read_b128 v[186:189], v225 offset:3072
	ds_read_b128 v[190:193], v225 offset:4096
	ds_read_b128 v[204:207], v225 offset:5120
	ds_read_b128 v[208:211], v225 offset:6144
	ds_read_b128 v[212:215], v225 offset:7168
	s_add_u32 s4, s0, 0x100
	s_addc_u32 s5, s1, 0
	s_add_i32 s58, 0, 0x10000
	s_cmp_eq_u32 s57, 28
	s_cselect_b32 s35, s27, s5
	s_cselect_b32 s34, s26, s4
	s_cselect_b32 s31, s25, s51
	s_cselect_b32 s30, s37, s50
	s_add_i32 s59, 0, 0x14000
	s_cmp_eq_u32 s33, 0
	s_cbranch_scc0 .Lpeel_skipA_0
	s_add_u32 vcc_lo, s0, 0xffffc000
	s_addc_u32 vcc_hi, s1, -1
	s_mov_b32 m0, s52
	s_nop 0
	global_load_lds_dwordx4 v158, vcc
	s_mov_b32 m0, s53
	s_nop 0
	global_load_lds_dwordx4 v160, vcc
	s_add_i32 m0, s38, 0xc000
	s_nop 0
	global_load_lds_dwordx4 v158, s[0:1]
	s_add_i32 m0, s38, 0xe000
	s_nop 0
	global_load_lds_dwordx4 v160, s[0:1]
.Lpeel_skipA_0:
	s_waitcnt vmcnt(8)
	s_waitcnt lgkmcnt(0)
	v_mfma_f32_16x16x32_bf16 v[126:129], v[130:133], v[174:177], 0
	v_mfma_f32_16x16x32_bf16 v[126:129], v[134:137], v[178:181], v[126:129]
	s_barrier
	s_setprio 1
	v_mfma_f32_16x16x32_bf16 v[122:125], v[142:145], v[178:181], 0
	v_mfma_f32_16x16x32_bf16 v[122:125], v[138:141], v[174:177], v[122:125]
	v_mfma_f32_16x16x32_bf16 v[106:109], v[138:141], v[182:185], 0
	v_mfma_f32_16x16x32_bf16 v[106:109], v[142:145], v[186:189], v[106:109]
	v_mfma_f32_16x16x32_bf16 v[110:113], v[134:137], v[186:189], 0
	v_mfma_f32_16x16x32_bf16 v[110:113], v[130:133], v[182:185], v[110:113]
	v_mfma_f32_16x16x32_bf16 v[94:97], v[130:133], v[190:193], 0
	v_mfma_f32_16x16x32_bf16 v[94:97], v[134:137], v[204:207], v[94:97]
	v_mfma_f32_16x16x32_bf16 v[90:93], v[142:145], v[204:207], 0
	v_mfma_f32_16x16x32_bf16 v[90:93], v[138:141], v[190:193], v[90:93]
	v_mfma_f32_16x16x32_bf16 v[74:77], v[138:141], v[208:211], 0
	v_mfma_f32_16x16x32_bf16 v[74:77], v[142:145], v[212:215], v[74:77]
	v_mfma_f32_16x16x32_bf16 v[78:81], v[134:137], v[212:215], 0
	v_mfma_f32_16x16x32_bf16 v[78:81], v[130:133], v[208:211], v[78:81]
	v_mfma_f32_16x16x32_bf16 v[118:121], v[146:149], v[174:177], 0
	v_mfma_f32_16x16x32_bf16 v[118:121], v[162:165], v[178:181], v[118:121]
	v_mfma_f32_16x16x32_bf16 v[114:117], v[170:173], v[178:181], 0
	v_mfma_f32_16x16x32_bf16 v[114:117], v[166:169], v[174:177], v[114:117]
	v_mfma_f32_16x16x32_bf16 v[98:101], v[166:169], v[182:185], 0
	v_mfma_f32_16x16x32_bf16 v[98:101], v[170:173], v[186:189], v[98:101]
	v_mfma_f32_16x16x32_bf16 v[102:105], v[162:165], v[186:189], 0
	v_mfma_f32_16x16x32_bf16 v[102:105], v[146:149], v[182:185], v[102:105]
	v_mfma_f32_16x16x32_bf16 v[86:89], v[146:149], v[190:193], 0
	v_mfma_f32_16x16x32_bf16 v[86:89], v[162:165], v[204:207], v[86:89]
	v_mfma_f32_16x16x32_bf16 v[82:85], v[170:173], v[204:207], 0
	v_mfma_f32_16x16x32_bf16 v[82:85], v[166:169], v[190:193], v[82:85]
	v_mfma_f32_16x16x32_bf16 v[66:69], v[166:169], v[208:211], 0
	v_mfma_f32_16x16x32_bf16 v[66:69], v[170:173], v[212:215], v[66:69]
	v_mfma_f32_16x16x32_bf16 v[70:73], v[162:165], v[212:215], 0
	v_mfma_f32_16x16x32_bf16 v[70:73], v[146:149], v[208:211], v[70:73]
	s_setprio 0
	s_barrier
	ds_read_b128 v[174:177], v225 offset:16384
	ds_read_b128 v[178:181], v225 offset:17408
	ds_read_b128 v[182:185], v225 offset:18432
	ds_read_b128 v[186:189], v225 offset:19456
	ds_read_b128 v[190:193], v225 offset:20480
	ds_read_b128 v[204:207], v225 offset:21504
	ds_read_b128 v[208:211], v225 offset:22528
	ds_read_b128 v[212:215], v225 offset:23552
	s_add_i32 s0, s58, s15
	s_mov_b32 m0, s0
	s_nop 0
	global_load_lds_dwordx4 v152, s[30:31]
	s_add_i32 m0, s0, 0x2000
	s_add_u32 s0, s30, 0x80000
	s_addc_u32 s1, s31, 0
	s_add_i32 s58, s59, s15
	global_load_lds_dwordx4 v156, s[30:31]
	s_mov_b32 m0, s58
	s_nop 0
	global_load_lds_dwordx4 v152, s[0:1]
	s_add_i32 m0, s58, 0x2000
	s_nop 0
	global_load_lds_dwordx4 v156, s[0:1]
	s_waitcnt vmcnt(6)
	s_waitcnt lgkmcnt(0)
	v_mfma_f32_16x16x32_bf16 v[62:65], v[130:133], v[174:177], 0
	v_mfma_f32_16x16x32_bf16 v[62:65], v[134:137], v[178:181], v[62:65]
	s_barrier
	s_setprio 1
	v_mfma_f32_16x16x32_bf16 v[58:61], v[142:145], v[178:181], 0
	v_mfma_f32_16x16x32_bf16 v[58:61], v[138:141], v[174:177], v[58:61]
	v_mfma_f32_16x16x32_bf16 v[42:45], v[138:141], v[182:185], 0
	v_mfma_f32_16x16x32_bf16 v[42:45], v[142:145], v[186:189], v[42:45]
	v_mfma_f32_16x16x32_bf16 v[46:49], v[134:137], v[186:189], 0
	v_mfma_f32_16x16x32_bf16 v[46:49], v[130:133], v[182:185], v[46:49]
	v_mfma_f32_16x16x32_bf16 v[30:33], v[130:133], v[190:193], 0
	v_mfma_f32_16x16x32_bf16 v[30:33], v[134:137], v[204:207], v[30:33]
	v_mfma_f32_16x16x32_bf16 v[26:29], v[142:145], v[204:207], 0
	v_mfma_f32_16x16x32_bf16 v[26:29], v[138:141], v[190:193], v[26:29]
	v_mfma_f32_16x16x32_bf16 v[10:13], v[138:141], v[208:211], 0
	v_mfma_f32_16x16x32_bf16 v[10:13], v[142:145], v[212:215], v[10:13]
	v_mfma_f32_16x16x32_bf16 v[14:17], v[134:137], v[212:215], 0
	v_mfma_f32_16x16x32_bf16 v[14:17], v[130:133], v[208:211], v[14:17]
	v_mfma_f32_16x16x32_bf16 v[54:57], v[146:149], v[174:177], 0
	v_mfma_f32_16x16x32_bf16 v[54:57], v[162:165], v[178:181], v[54:57]
	v_mfma_f32_16x16x32_bf16 v[50:53], v[170:173], v[178:181], 0
	v_mfma_f32_16x16x32_bf16 v[50:53], v[166:169], v[174:177], v[50:53]
	v_mfma_f32_16x16x32_bf16 v[34:37], v[166:169], v[182:185], 0
	v_mfma_f32_16x16x32_bf16 v[34:37], v[170:173], v[186:189], v[34:37]
	v_mfma_f32_16x16x32_bf16 v[38:41], v[162:165], v[186:189], 0
	v_mfma_f32_16x16x32_bf16 v[38:41], v[146:149], v[182:185], v[38:41]
	v_mfma_f32_16x16x32_bf16 v[22:25], v[146:149], v[190:193], 0
	v_mfma_f32_16x16x32_bf16 v[22:25], v[162:165], v[204:207], v[22:25]
	v_mfma_f32_16x16x32_bf16 v[18:21], v[170:173], v[204:207], 0
	v_mfma_f32_16x16x32_bf16 v[18:21], v[166:169], v[190:193], v[18:21]
	v_mfma_f32_16x16x32_bf16 v[2:5], v[166:169], v[208:211], 0
	v_mfma_f32_16x16x32_bf16 v[2:5], v[170:173], v[212:215], v[2:5]
	v_mfma_f32_16x16x32_bf16 v[6:9], v[162:165], v[212:215], 0
	v_mfma_f32_16x16x32_bf16 v[6:9], v[146:149], v[208:211], v[6:9]
	s_setprio 0
	s_barrier
	s_mov_b32 m0, s38
	s_nop 0
	global_load_lds_dwordx4 v150, s[34:35]
	s_mov_b32 m0, s39
	s_nop 0
	global_load_lds_dwordx4 v154, s[34:35]
	ds_read_b128 v[130:133], v224 offset:32768
	ds_read_b128 v[134:137], v224 offset:33792
	ds_read_b128 v[138:141], v224 offset:34816
	ds_read_b128 v[142:145], v224 offset:35840
	ds_read_b128 v[146:149], v224 offset:49152
	ds_read_b128 v[162:165], v224 offset:50176
	ds_read_b128 v[166:169], v224 offset:51200
	ds_read_b128 v[170:173], v224 offset:52224
	ds_read_b128 v[174:177], v225 offset:32768
	ds_read_b128 v[178:181], v225 offset:33792
	ds_read_b128 v[182:185], v225 offset:34816
	ds_read_b128 v[186:189], v225 offset:35840
	ds_read_b128 v[190:193], v225 offset:36864
	ds_read_b128 v[204:207], v225 offset:37888
	ds_read_b128 v[208:211], v225 offset:38912
	ds_read_b128 v[212:215], v225 offset:39936
	s_add_i32 s58, 0, 0x18000
	s_add_i32 s59, 0, 0x1c000
	s_add_u32 s0, s34, 0x4000
	s_addc_u32 s1, s35, 0
	s_mov_b32 m0, s40
	s_nop 0
	global_load_lds_dwordx4 v150, s[0:1]
	s_mov_b32 m0, s41
	s_nop 0
	global_load_lds_dwordx4 v154, s[0:1]
	s_waitcnt vmcnt(8)
	s_waitcnt lgkmcnt(0)
	v_mfma_f32_16x16x32_bf16 v[126:129], v[130:133], v[174:177], v[126:129]
	v_mfma_f32_16x16x32_bf16 v[126:129], v[134:137], v[178:181], v[126:129]
	s_barrier
	s_setprio 1
	v_mfma_f32_16x16x32_bf16 v[122:125], v[142:145], v[178:181], v[122:125]
	v_mfma_f32_16x16x32_bf16 v[122:125], v[138:141], v[174:177], v[122:125]
	v_mfma_f32_16x16x32_bf16 v[106:109], v[138:141], v[182:185], v[106:109]
	v_mfma_f32_16x16x32_bf16 v[106:109], v[142:145], v[186:189], v[106:109]
	v_mfma_f32_16x16x32_bf16 v[110:113], v[134:137], v[186:189], v[110:113]
	v_mfma_f32_16x16x32_bf16 v[110:113], v[130:133], v[182:185], v[110:113]
	v_mfma_f32_16x16x32_bf16 v[94:97], v[130:133], v[190:193], v[94:97]
	v_mfma_f32_16x16x32_bf16 v[94:97], v[134:137], v[204:207], v[94:97]
	v_mfma_f32_16x16x32_bf16 v[90:93], v[142:145], v[204:207], v[90:93]
	v_mfma_f32_16x16x32_bf16 v[90:93], v[138:141], v[190:193], v[90:93]
	v_mfma_f32_16x16x32_bf16 v[74:77], v[138:141], v[208:211], v[74:77]
	v_mfma_f32_16x16x32_bf16 v[74:77], v[142:145], v[212:215], v[74:77]
	v_mfma_f32_16x16x32_bf16 v[78:81], v[134:137], v[212:215], v[78:81]
	v_mfma_f32_16x16x32_bf16 v[78:81], v[130:133], v[208:211], v[78:81]
	v_mfma_f32_16x16x32_bf16 v[118:121], v[146:149], v[174:177], v[118:121]
	v_mfma_f32_16x16x32_bf16 v[118:121], v[162:165], v[178:181], v[118:121]
	v_mfma_f32_16x16x32_bf16 v[114:117], v[170:173], v[178:181], v[114:117]
	v_mfma_f32_16x16x32_bf16 v[114:117], v[166:169], v[174:177], v[114:117]
	v_mfma_f32_16x16x32_bf16 v[98:101], v[166:169], v[182:185], v[98:101]
	v_mfma_f32_16x16x32_bf16 v[98:101], v[170:173], v[186:189], v[98:101]
	v_mfma_f32_16x16x32_bf16 v[102:105], v[162:165], v[186:189], v[102:105]
	v_mfma_f32_16x16x32_bf16 v[102:105], v[146:149], v[182:185], v[102:105]
	v_mfma_f32_16x16x32_bf16 v[86:89], v[146:149], v[190:193], v[86:89]
	v_mfma_f32_16x16x32_bf16 v[86:89], v[162:165], v[204:207], v[86:89]
	v_mfma_f32_16x16x32_bf16 v[82:85], v[170:173], v[204:207], v[82:85]
	v_mfma_f32_16x16x32_bf16 v[82:85], v[166:169], v[190:193], v[82:85]
	v_mfma_f32_16x16x32_bf16 v[66:69], v[166:169], v[208:211], v[66:69]
	v_mfma_f32_16x16x32_bf16 v[66:69], v[170:173], v[212:215], v[66:69]
	v_mfma_f32_16x16x32_bf16 v[70:73], v[162:165], v[212:215], v[70:73]
	v_mfma_f32_16x16x32_bf16 v[70:73], v[146:149], v[208:211], v[70:73]
	s_setprio 0
	s_barrier
	ds_read_b128 v[174:177], v225 offset:49152
	ds_read_b128 v[178:181], v225 offset:50176
	ds_read_b128 v[182:185], v225 offset:51200
	ds_read_b128 v[186:189], v225 offset:52224
	ds_read_b128 v[190:193], v225 offset:53248
	ds_read_b128 v[204:207], v225 offset:54272
	ds_read_b128 v[208:211], v225 offset:55296
	ds_read_b128 v[212:215], v225 offset:56320
	s_add_i32 s0, s58, s15
	s_add_u32 vcc_lo, s30, s94
	s_addc_u32 vcc_hi, s31, s95
	s_mov_b32 m0, s0
	s_nop 0
	global_load_lds_dwordx4 v152, vcc
	s_add_i32 m0, s0, 0x2000
	s_add_u32 s0, s30, 0x80080
	s_addc_u32 s1, s31, 0
	s_add_i32 s30, s59, s15
	global_load_lds_dwordx4 v156, vcc
	s_mov_b32 m0, s30
	s_nop 0
	global_load_lds_dwordx4 v152, s[0:1]
	s_add_i32 m0, s30, 0x2000
	s_nop 0
	global_load_lds_dwordx4 v156, s[0:1]
	s_waitcnt vmcnt(6)
	s_waitcnt lgkmcnt(0)
	v_mfma_f32_16x16x32_bf16 v[62:65], v[130:133], v[174:177], v[62:65]
	v_mfma_f32_16x16x32_bf16 v[62:65], v[134:137], v[178:181], v[62:65]
	s_barrier
	s_setprio 1
	v_mfma_f32_16x16x32_bf16 v[58:61], v[142:145], v[178:181], v[58:61]
	v_mfma_f32_16x16x32_bf16 v[58:61], v[138:141], v[174:177], v[58:61]
	v_mfma_f32_16x16x32_bf16 v[42:45], v[138:141], v[182:185], v[42:45]
	v_mfma_f32_16x16x32_bf16 v[42:45], v[142:145], v[186:189], v[42:45]
	v_mfma_f32_16x16x32_bf16 v[46:49], v[134:137], v[186:189], v[46:49]
	v_mfma_f32_16x16x32_bf16 v[46:49], v[130:133], v[182:185], v[46:49]
	v_mfma_f32_16x16x32_bf16 v[30:33], v[130:133], v[190:193], v[30:33]
	v_mfma_f32_16x16x32_bf16 v[30:33], v[134:137], v[204:207], v[30:33]
	v_mfma_f32_16x16x32_bf16 v[26:29], v[142:145], v[204:207], v[26:29]
	v_mfma_f32_16x16x32_bf16 v[26:29], v[138:141], v[190:193], v[26:29]
	v_mfma_f32_16x16x32_bf16 v[10:13], v[138:141], v[208:211], v[10:13]
	v_mfma_f32_16x16x32_bf16 v[10:13], v[142:145], v[212:215], v[10:13]
	s_add_i32 s57, s57, 2
	v_mfma_f32_16x16x32_bf16 v[14:17], v[134:137], v[212:215], v[14:17]
	v_mfma_f32_16x16x32_bf16 v[14:17], v[130:133], v[208:211], v[14:17]
	s_add_u32 s50, s50, 0x100
	v_mfma_f32_16x16x32_bf16 v[54:57], v[146:149], v[174:177], v[54:57]
	v_mfma_f32_16x16x32_bf16 v[54:57], v[162:165], v[178:181], v[54:57]
	s_addc_u32 s51, s51, 0
	v_mfma_f32_16x16x32_bf16 v[50:53], v[170:173], v[178:181], v[50:53]
	v_mfma_f32_16x16x32_bf16 v[50:53], v[166:169], v[174:177], v[50:53]
	s_cmp_gt_u32 s57, 29
	v_mfma_f32_16x16x32_bf16 v[34:37], v[166:169], v[182:185], v[34:37]
	v_mfma_f32_16x16x32_bf16 v[34:37], v[170:173], v[186:189], v[34:37]
	s_mov_b64 s[0:1], s[4:5]
	v_mfma_f32_16x16x32_bf16 v[38:41], v[162:165], v[186:189], v[38:41]
	v_mfma_f32_16x16x32_bf16 v[38:41], v[146:149], v[182:185], v[38:41]
	v_mfma_f32_16x16x32_bf16 v[22:25], v[146:149], v[190:193], v[22:25]
	v_mfma_f32_16x16x32_bf16 v[22:25], v[162:165], v[204:207], v[22:25]
	v_mfma_f32_16x16x32_bf16 v[18:21], v[170:173], v[204:207], v[18:21]
	v_mfma_f32_16x16x32_bf16 v[18:21], v[166:169], v[190:193], v[18:21]
	v_mfma_f32_16x16x32_bf16 v[2:5], v[166:169], v[208:211], v[2:5]
	v_mfma_f32_16x16x32_bf16 v[2:5], v[170:173], v[212:215], v[2:5]
	v_mfma_f32_16x16x32_bf16 v[6:9], v[162:165], v[212:215], v[6:9]
	v_mfma_f32_16x16x32_bf16 v[6:9], v[146:149], v[208:211], v[6:9]
	s_setprio 0
	s_barrier
	s_cbranch_scc1 .Lpeel_exit_0

.Lpeel_exit_0:
	s_add_u32 vcc_lo, s26, 0xffffc000
	s_addc_u32 vcc_hi, s27, -1
	s_mov_b32 m0, s52
	s_nop 0
	global_load_lds_dwordx4 v158, vcc
	s_mov_b32 m0, s53
	s_nop 0
	global_load_lds_dwordx4 v160, vcc
	s_add_i32 m0, s38, 0xc000
	s_nop 0
	global_load_lds_dwordx4 v158, s[26:27]
	s_add_i32 m0, s38, 0xe000
	s_nop 0
	global_load_lds_dwordx4 v160, s[26:27]

.LBB0_529:
	s_lshl_b32 s10, s30, 8
	s_ashr_i32 s11, s10, 31
	s_lshl_b64 s[10:11], s[10:11], 12
	s_add_u32 s10, s86, s10
	s_addc_u32 s11, s87, s11
	s_and_b64 s[12:13], s[2:3], exec
	s_cselect_b32 s34, s11, s15
	s_cselect_b32 s35, s10, s14
	s_ashr_i32 s9, s8, 31
	s_lshl_b64 s[12:13], s[8:9], 20
	v_readlane_b32 s9, v254, 62
	s_add_u32 s12, s9, s12
	v_readlane_b32 s9, v254, 63
	s_addc_u32 s13, s9, s13
	s_and_b64 s[18:19], s[2:3], exec
	s_cselect_b32 s9, s13, s17
	s_cselect_b32 s36, s12, s16
	s_add_u32 s14, s14, 0x80080
	s_addc_u32 s15, s15, 0
	s_add_u32 s37, s16, 0x100
	s_addc_u32 s38, s17, 0
	s_mov_b32 s39, -2
	ds_read_b128 v[152:155], v145
	ds_read_b128 v[156:159], v145 offset:1024
	ds_read_b128 v[160:163], v145 offset:2048
	ds_read_b128 v[164:167], v145 offset:3072
	ds_read_b128 v[168:171], v145 offset:16384
	ds_read_b128 v[172:175], v145 offset:17408
	ds_read_b128 v[176:179], v145 offset:18432
	ds_read_b128 v[180:183], v145 offset:19456
	ds_read_b128 v[184:187], v151
	ds_read_b128 v[188:191], v151 offset:1024
	ds_read_b128 v[204:207], v151 offset:2048
	ds_read_b128 v[208:211], v151 offset:3072
	ds_read_b128 v[212:215], v151 offset:4096
	ds_read_b128 v[216:219], v151 offset:5120
	ds_read_b128 v[220:223], v151 offset:6144
	ds_read_b128 v[224:227], v151 offset:7168
	s_add_u32 s16, s14, 0xfff80080
	s_addc_u32 s17, s15, -1
	s_add_i32 s40, 0, 0x10000
	s_cmp_eq_u32 s39, 28
	s_cselect_b32 s19, s34, s17
	s_cselect_b32 s18, s35, s16
	s_cselect_b32 s17, s9, s38
	s_cselect_b32 s16, s36, s37
	s_add_i32 s42, 0, 0x14000
	s_cmp_eq_u32 s29, 1
	s_cbranch_scc0 .Lpeel_skipA_2
	s_add_u32 vcc_lo, s14, 0xfff80000
	s_addc_u32 vcc_hi, s15, -1
	s_mov_b32 m0, s27
	s_nop 0
	global_load_lds_dwordx4 v138, vcc
	s_mov_b32 m0, s28
	s_nop 0
	global_load_lds_dwordx4 v140, vcc
	s_add_i32 m0, s23, 0xc000
	s_nop 0
	global_load_lds_dwordx4 v138, s[14:15]
	s_add_i32 m0, s23, 0xe000
	s_nop 0
	global_load_lds_dwordx4 v140, s[14:15]
.Lpeel_skipA_2:
	s_waitcnt vmcnt(20)
	s_waitcnt lgkmcnt(0)
	v_mfma_f32_16x16x32_bf16 v[126:129], v[152:155], v[184:187], 0
	v_mfma_f32_16x16x32_bf16 v[126:129], v[156:159], v[188:191], v[126:129]
	s_barrier
	s_setprio 1
	v_mfma_f32_16x16x32_bf16 v[122:125], v[164:167], v[188:191], 0
	v_mfma_f32_16x16x32_bf16 v[122:125], v[160:163], v[184:187], v[122:125]
	v_mfma_f32_16x16x32_bf16 v[106:109], v[160:163], v[204:207], 0
	v_mfma_f32_16x16x32_bf16 v[106:109], v[164:167], v[208:211], v[106:109]
	v_mfma_f32_16x16x32_bf16 v[110:113], v[156:159], v[208:211], 0
	v_mfma_f32_16x16x32_bf16 v[110:113], v[152:155], v[204:207], v[110:113]
	v_mfma_f32_16x16x32_bf16 v[94:97], v[152:155], v[212:215], 0
	v_mfma_f32_16x16x32_bf16 v[94:97], v[156:159], v[216:219], v[94:97]
	v_mfma_f32_16x16x32_bf16 v[90:93], v[164:167], v[216:219], 0
	v_mfma_f32_16x16x32_bf16 v[90:93], v[160:163], v[212:215], v[90:93]
	v_mfma_f32_16x16x32_bf16 v[74:77], v[160:163], v[220:223], 0
	v_mfma_f32_16x16x32_bf16 v[74:77], v[164:167], v[224:227], v[74:77]
	v_mfma_f32_16x16x32_bf16 v[78:81], v[156:159], v[224:227], 0
	v_mfma_f32_16x16x32_bf16 v[78:81], v[152:155], v[220:223], v[78:81]
	v_mfma_f32_16x16x32_bf16 v[118:121], v[168:171], v[184:187], 0
	v_mfma_f32_16x16x32_bf16 v[118:121], v[172:175], v[188:191], v[118:121]
	v_mfma_f32_16x16x32_bf16 v[114:117], v[180:183], v[188:191], 0
	v_mfma_f32_16x16x32_bf16 v[114:117], v[176:179], v[184:187], v[114:117]
	v_mfma_f32_16x16x32_bf16 v[98:101], v[176:179], v[204:207], 0
	v_mfma_f32_16x16x32_bf16 v[98:101], v[180:183], v[208:211], v[98:101]
	v_mfma_f32_16x16x32_bf16 v[102:105], v[172:175], v[208:211], 0
	v_mfma_f32_16x16x32_bf16 v[102:105], v[168:171], v[204:207], v[102:105]
	v_mfma_f32_16x16x32_bf16 v[86:89], v[168:171], v[212:215], 0
	v_mfma_f32_16x16x32_bf16 v[86:89], v[172:175], v[216:219], v[86:89]
	v_mfma_f32_16x16x32_bf16 v[82:85], v[180:183], v[216:219], 0
	v_mfma_f32_16x16x32_bf16 v[82:85], v[176:179], v[212:215], v[82:85]
	v_mfma_f32_16x16x32_bf16 v[66:69], v[176:179], v[220:223], 0
	v_mfma_f32_16x16x32_bf16 v[66:69], v[180:183], v[224:227], v[66:69]
	v_mfma_f32_16x16x32_bf16 v[70:73], v[172:175], v[224:227], 0
	v_mfma_f32_16x16x32_bf16 v[70:73], v[168:171], v[220:223], v[70:73]
	s_setprio 0
	s_barrier
	ds_read_b128 v[184:187], v151 offset:16384
	ds_read_b128 v[188:191], v151 offset:17408
	ds_read_b128 v[204:207], v151 offset:18432
	ds_read_b128 v[208:211], v151 offset:19456
	ds_read_b128 v[212:215], v151 offset:20480
	ds_read_b128 v[216:219], v151 offset:21504
	ds_read_b128 v[220:223], v151 offset:22528
	ds_read_b128 v[224:227], v151 offset:23552
	s_add_i32 s40, s40, s22
	s_mov_b32 m0, s40
	s_nop 0
	global_load_lds_dwordx4 v134, s[16:17]
	s_add_i32 m0, s40, 0x2000
	s_add_u32 s40, s16, 0x80000
	s_addc_u32 s41, s17, 0
	s_add_i32 s42, s42, s22
	global_load_lds_dwordx4 v130, s[16:17]
	s_mov_b32 m0, s42
	s_nop 0
	global_load_lds_dwordx4 v134, s[40:41]
	s_add_i32 m0, s42, 0x2000
	s_nop 0
	global_load_lds_dwordx4 v130, s[40:41]
	s_waitcnt vmcnt(6)
	s_waitcnt lgkmcnt(0)
	v_mfma_f32_16x16x32_bf16 v[62:65], v[152:155], v[184:187], 0
	v_mfma_f32_16x16x32_bf16 v[62:65], v[156:159], v[188:191], v[62:65]
	s_barrier
	s_setprio 1
	v_mfma_f32_16x16x32_bf16 v[58:61], v[164:167], v[188:191], 0
	v_mfma_f32_16x16x32_bf16 v[58:61], v[160:163], v[184:187], v[58:61]
	v_mfma_f32_16x16x32_bf16 v[42:45], v[160:163], v[204:207], 0
	v_mfma_f32_16x16x32_bf16 v[42:45], v[164:167], v[208:211], v[42:45]
	v_mfma_f32_16x16x32_bf16 v[46:49], v[156:159], v[208:211], 0
	v_mfma_f32_16x16x32_bf16 v[46:49], v[152:155], v[204:207], v[46:49]
	v_mfma_f32_16x16x32_bf16 v[30:33], v[152:155], v[212:215], 0
	v_mfma_f32_16x16x32_bf16 v[30:33], v[156:159], v[216:219], v[30:33]
	v_mfma_f32_16x16x32_bf16 v[26:29], v[164:167], v[216:219], 0
	v_mfma_f32_16x16x32_bf16 v[26:29], v[160:163], v[212:215], v[26:29]
	v_mfma_f32_16x16x32_bf16 v[10:13], v[160:163], v[220:223], 0
	v_mfma_f32_16x16x32_bf16 v[10:13], v[164:167], v[224:227], v[10:13]
	v_mfma_f32_16x16x32_bf16 v[14:17], v[156:159], v[224:227], 0
	v_mfma_f32_16x16x32_bf16 v[14:17], v[152:155], v[220:223], v[14:17]
	v_mfma_f32_16x16x32_bf16 v[54:57], v[168:171], v[184:187], 0
	v_mfma_f32_16x16x32_bf16 v[54:57], v[172:175], v[188:191], v[54:57]
	v_mfma_f32_16x16x32_bf16 v[50:53], v[180:183], v[188:191], 0
	v_mfma_f32_16x16x32_bf16 v[50:53], v[176:179], v[184:187], v[50:53]
	v_mfma_f32_16x16x32_bf16 v[34:37], v[176:179], v[204:207], 0
	v_mfma_f32_16x16x32_bf16 v[34:37], v[180:183], v[208:211], v[34:37]
	v_mfma_f32_16x16x32_bf16 v[38:41], v[172:175], v[208:211], 0
	v_mfma_f32_16x16x32_bf16 v[38:41], v[168:171], v[204:207], v[38:41]
	v_mfma_f32_16x16x32_bf16 v[22:25], v[168:171], v[212:215], 0
	v_mfma_f32_16x16x32_bf16 v[22:25], v[172:175], v[216:219], v[22:25]
	v_mfma_f32_16x16x32_bf16 v[18:21], v[180:183], v[216:219], 0
	v_mfma_f32_16x16x32_bf16 v[18:21], v[176:179], v[212:215], v[18:21]
	v_mfma_f32_16x16x32_bf16 v[2:5], v[176:179], v[220:223], 0
	v_mfma_f32_16x16x32_bf16 v[2:5], v[180:183], v[224:227], v[2:5]
	v_mfma_f32_16x16x32_bf16 v[6:9], v[172:175], v[224:227], 0
	v_mfma_f32_16x16x32_bf16 v[6:9], v[168:171], v[220:223], v[6:9]
	s_setprio 0
	s_barrier
	s_mov_b32 m0, s23
	s_nop 0
	global_load_lds_dwordx4 v136, s[18:19]
	s_mov_b32 m0, s24
	s_nop 0
	global_load_lds_dwordx4 v132, s[18:19]
	ds_read_b128 v[152:155], v145 offset:32768
	ds_read_b128 v[156:159], v145 offset:33792
	ds_read_b128 v[160:163], v145 offset:34816
	ds_read_b128 v[164:167], v145 offset:35840
	ds_read_b128 v[168:171], v145 offset:49152
	ds_read_b128 v[172:175], v145 offset:50176
	ds_read_b128 v[176:179], v145 offset:51200
	ds_read_b128 v[180:183], v145 offset:52224
	ds_read_b128 v[184:187], v151 offset:32768
	ds_read_b128 v[188:191], v151 offset:33792
	ds_read_b128 v[204:207], v151 offset:34816
	ds_read_b128 v[208:211], v151 offset:35840
	ds_read_b128 v[212:215], v151 offset:36864
	ds_read_b128 v[216:219], v151 offset:37888
	ds_read_b128 v[220:223], v151 offset:38912
	ds_read_b128 v[224:227], v151 offset:39936
	s_add_i32 s40, 0, 0x18000
	s_add_i32 s41, 0, 0x1c000
	s_add_u32 s18, s18, 0x80000
	s_addc_u32 s19, s19, 0
	s_mov_b32 m0, s25
	s_nop 0
	global_load_lds_dwordx4 v136, s[18:19]
	s_mov_b32 m0, s26
	s_nop 0
	global_load_lds_dwordx4 v132, s[18:19]
	s_waitcnt vmcnt(8)
	s_waitcnt lgkmcnt(0)
	v_mfma_f32_16x16x32_bf16 v[126:129], v[152:155], v[184:187], v[126:129]
	v_mfma_f32_16x16x32_bf16 v[126:129], v[156:159], v[188:191], v[126:129]
	s_barrier
	s_setprio 1
	v_mfma_f32_16x16x32_bf16 v[122:125], v[164:167], v[188:191], v[122:125]
	v_mfma_f32_16x16x32_bf16 v[122:125], v[160:163], v[184:187], v[122:125]
	v_mfma_f32_16x16x32_bf16 v[106:109], v[160:163], v[204:207], v[106:109]
	v_mfma_f32_16x16x32_bf16 v[106:109], v[164:167], v[208:211], v[106:109]
	v_mfma_f32_16x16x32_bf16 v[110:113], v[156:159], v[208:211], v[110:113]
	v_mfma_f32_16x16x32_bf16 v[110:113], v[152:155], v[204:207], v[110:113]
	v_mfma_f32_16x16x32_bf16 v[94:97], v[152:155], v[212:215], v[94:97]
	v_mfma_f32_16x16x32_bf16 v[94:97], v[156:159], v[216:219], v[94:97]
	v_mfma_f32_16x16x32_bf16 v[90:93], v[164:167], v[216:219], v[90:93]
	v_mfma_f32_16x16x32_bf16 v[90:93], v[160:163], v[212:215], v[90:93]
	v_mfma_f32_16x16x32_bf16 v[74:77], v[160:163], v[220:223], v[74:77]
	v_mfma_f32_16x16x32_bf16 v[74:77], v[164:167], v[224:227], v[74:77]
	v_mfma_f32_16x16x32_bf16 v[78:81], v[156:159], v[224:227], v[78:81]
	v_mfma_f32_16x16x32_bf16 v[78:81], v[152:155], v[220:223], v[78:81]
	v_mfma_f32_16x16x32_bf16 v[118:121], v[168:171], v[184:187], v[118:121]
	v_mfma_f32_16x16x32_bf16 v[118:121], v[172:175], v[188:191], v[118:121]
	v_mfma_f32_16x16x32_bf16 v[114:117], v[180:183], v[188:191], v[114:117]
	v_mfma_f32_16x16x32_bf16 v[114:117], v[176:179], v[184:187], v[114:117]
	v_mfma_f32_16x16x32_bf16 v[98:101], v[176:179], v[204:207], v[98:101]
	v_mfma_f32_16x16x32_bf16 v[98:101], v[180:183], v[208:211], v[98:101]
	v_mfma_f32_16x16x32_bf16 v[102:105], v[172:175], v[208:211], v[102:105]
	v_mfma_f32_16x16x32_bf16 v[102:105], v[168:171], v[204:207], v[102:105]
	v_mfma_f32_16x16x32_bf16 v[86:89], v[168:171], v[212:215], v[86:89]
	v_mfma_f32_16x16x32_bf16 v[86:89], v[172:175], v[216:219], v[86:89]
	v_mfma_f32_16x16x32_bf16 v[82:85], v[180:183], v[216:219], v[82:85]
	v_mfma_f32_16x16x32_bf16 v[82:85], v[176:179], v[212:215], v[82:85]
	v_mfma_f32_16x16x32_bf16 v[66:69], v[176:179], v[220:223], v[66:69]
	v_mfma_f32_16x16x32_bf16 v[66:69], v[180:183], v[224:227], v[66:69]
	v_mfma_f32_16x16x32_bf16 v[70:73], v[172:175], v[224:227], v[70:73]
	v_mfma_f32_16x16x32_bf16 v[70:73], v[168:171], v[220:223], v[70:73]
	s_setprio 0
	s_barrier
	ds_read_b128 v[184:187], v151 offset:49152
	ds_read_b128 v[188:191], v151 offset:50176
	ds_read_b128 v[204:207], v151 offset:51200
	ds_read_b128 v[208:211], v151 offset:52224
	ds_read_b128 v[212:215], v151 offset:53248
	ds_read_b128 v[216:219], v151 offset:54272
	ds_read_b128 v[220:223], v151 offset:55296
	ds_read_b128 v[224:227], v151 offset:56320
	s_add_i32 s18, s40, s22
	s_add_u32 vcc_lo, s16, s94
	s_addc_u32 vcc_hi, s17, s95
	s_mov_b32 m0, s18
	s_nop 0
	global_load_lds_dwordx4 v134, vcc
	s_add_i32 m0, s18, 0x2000
	s_add_u32 s16, s16, 0x80080
	s_addc_u32 s17, s17, 0
	s_add_i32 s18, s41, s22
	global_load_lds_dwordx4 v130, vcc
	s_mov_b32 m0, s18
	s_nop 0
	global_load_lds_dwordx4 v134, s[16:17]
	s_add_i32 m0, s18, 0x2000
	s_nop 0
	global_load_lds_dwordx4 v130, s[16:17]
	s_waitcnt vmcnt(6)
	s_waitcnt lgkmcnt(0)
	v_mfma_f32_16x16x32_bf16 v[62:65], v[152:155], v[184:187], v[62:65]
	v_mfma_f32_16x16x32_bf16 v[62:65], v[156:159], v[188:191], v[62:65]
	s_barrier
	s_setprio 1
	v_mfma_f32_16x16x32_bf16 v[58:61], v[164:167], v[188:191], v[58:61]
	v_mfma_f32_16x16x32_bf16 v[58:61], v[160:163], v[184:187], v[58:61]
	v_mfma_f32_16x16x32_bf16 v[42:45], v[160:163], v[204:207], v[42:45]
	v_mfma_f32_16x16x32_bf16 v[42:45], v[164:167], v[208:211], v[42:45]
	v_mfma_f32_16x16x32_bf16 v[46:49], v[156:159], v[208:211], v[46:49]
	v_mfma_f32_16x16x32_bf16 v[46:49], v[152:155], v[204:207], v[46:49]
	v_mfma_f32_16x16x32_bf16 v[30:33], v[152:155], v[212:215], v[30:33]
	v_mfma_f32_16x16x32_bf16 v[30:33], v[156:159], v[216:219], v[30:33]
	v_mfma_f32_16x16x32_bf16 v[26:29], v[164:167], v[216:219], v[26:29]
	v_mfma_f32_16x16x32_bf16 v[26:29], v[160:163], v[212:215], v[26:29]
	v_mfma_f32_16x16x32_bf16 v[10:13], v[160:163], v[220:223], v[10:13]
	v_mfma_f32_16x16x32_bf16 v[10:13], v[164:167], v[224:227], v[10:13]
	s_add_i32 s39, s39, 2
	v_mfma_f32_16x16x32_bf16 v[14:17], v[156:159], v[224:227], v[14:17]
	v_mfma_f32_16x16x32_bf16 v[14:17], v[152:155], v[220:223], v[14:17]
	s_add_u32 s14, s14, 0x100
	v_mfma_f32_16x16x32_bf16 v[54:57], v[168:171], v[184:187], v[54:57]
	v_mfma_f32_16x16x32_bf16 v[54:57], v[172:175], v[188:191], v[54:57]
	s_addc_u32 s15, s15, 0
	v_mfma_f32_16x16x32_bf16 v[50:53], v[180:183], v[188:191], v[50:53]
	v_mfma_f32_16x16x32_bf16 v[50:53], v[176:179], v[184:187], v[50:53]
	s_add_u32 s37, s37, 0x100
	v_mfma_f32_16x16x32_bf16 v[34:37], v[176:179], v[204:207], v[34:37]
	v_mfma_f32_16x16x32_bf16 v[34:37], v[180:183], v[208:211], v[34:37]
	s_addc_u32 s38, s38, 0
	v_mfma_f32_16x16x32_bf16 v[38:41], v[172:175], v[208:211], v[38:41]
	v_mfma_f32_16x16x32_bf16 v[38:41], v[168:171], v[204:207], v[38:41]
	s_cmp_gt_u32 s39, 29
	v_mfma_f32_16x16x32_bf16 v[22:25], v[168:171], v[212:215], v[22:25]
	v_mfma_f32_16x16x32_bf16 v[22:25], v[172:175], v[216:219], v[22:25]
	v_mfma_f32_16x16x32_bf16 v[18:21], v[180:183], v[216:219], v[18:21]
	v_mfma_f32_16x16x32_bf16 v[18:21], v[176:179], v[212:215], v[18:21]
	v_mfma_f32_16x16x32_bf16 v[2:5], v[176:179], v[220:223], v[2:5]
	v_mfma_f32_16x16x32_bf16 v[2:5], v[180:183], v[224:227], v[2:5]
	v_mfma_f32_16x16x32_bf16 v[6:9], v[172:175], v[224:227], v[6:9]
	v_mfma_f32_16x16x32_bf16 v[6:9], v[168:171], v[220:223], v[6:9]
	s_setprio 0
	s_barrier
	s_cbranch_scc1 .Lpeel_exit_2

.Lpeel_exit_2:
	s_add_u32 vcc_lo, s10, 0x80080
	s_addc_u32 vcc_hi, s11, 0
	s_add_u32 vcc_lo, vcc_lo, 0xfff80000
	s_addc_u32 vcc_hi, vcc_hi, -1
	s_mov_b32 m0, s27
	s_nop 0
	global_load_lds_dwordx4 v138, vcc
	s_mov_b32 m0, s28
	s_nop 0
	global_load_lds_dwordx4 v140, vcc
	s_add_u32 vcc_lo, s10, 0x80080
	s_addc_u32 vcc_hi, s11, 0
	s_add_i32 m0, s23, 0xc000
	s_nop 0
	global_load_lds_dwordx4 v138, vcc
	s_add_i32 m0, s23, 0xe000
	s_nop 0
	global_load_lds_dwordx4 v140, vcc

.LBB0_849:
	s_add_u32 s18, s18, 0x80
	s_addc_u32 s19, s19, 0
	s_add_u32 s51, s20, 0x100
	s_waitcnt lgkmcnt(0)
	s_waitcnt vmcnt(0)
	s_addc_u32 s54, s21, 0
	s_mov_b32 s20, 0
	ds_read_b128 v[66:69], v198
	ds_read_b128 v[78:81], v198 offset:1024
	ds_read_b128 v[82:85], v198 offset:2048
	ds_read_b128 v[98:101], v198 offset:3072
	ds_read_b128 v[106:109], v198 offset:16384
	ds_read_b128 v[118:121], v198 offset:17408
	ds_read_b128 v[130:133], v198 offset:18432
	ds_read_b128 v[142:145], v198 offset:19456
	ds_read_b128 v[150:153], v234
	ds_read_b128 v[154:157], v234 offset:1024
	ds_read_b128 v[158:161], v234 offset:2048
	ds_read_b128 v[162:165], v234 offset:3072
	ds_read_b128 v[170:173], v234 offset:4096
	ds_read_b128 v[174:177], v234 offset:5120
	ds_read_b128 v[178:181], v234 offset:6144
	ds_read_b128 v[190:193], v234 offset:7168
	s_add_i32 s55, s20, 2
	s_add_u32 s56, s18, 0x80
	s_addc_u32 s21, s19, 0
	s_add_i32 s58, 0, 0x10000
	s_cmp_eq_u32 s35, s20
	s_cselect_b32 s21, s1, s21
	s_cselect_b32 s20, s0, s56
	s_cselect_b32 s57, s17, s54
	s_cselect_b32 s56, s16, s51
	s_add_i32 s59, 0, 0x14000
	s_cmp_eq_u32 s36, 1
	s_cbranch_scc0 .Lpeel_skipA_5
	s_sub_u32 vcc_lo, s18, s12
	s_subb_u32 vcc_hi, s19, 0
	s_mov_b32 m0, s33
	s_nop 0
	global_load_lds_dwordx4 v210, vcc
	s_mov_b32 m0, s34
	s_nop 0
	global_load_lds_dwordx4 v212, vcc
	s_add_i32 m0, s26, 0xc000
	s_nop 0
	global_load_lds_dwordx4 v210, s[18:19]
	s_add_i32 m0, s26, 0xe000
	s_nop 0
	global_load_lds_dwordx4 v212, s[18:19]
.Lpeel_skipA_5:
	s_waitcnt vmcnt(28)
	s_waitcnt lgkmcnt(0)
	v_mfma_f32_16x16x32_bf16 v[186:189], v[66:69], v[150:153], 0
	v_mfma_f32_16x16x32_bf16 v[186:189], v[78:81], v[154:157], v[186:189]
	s_barrier
	s_setprio 1
	v_mfma_f32_16x16x32_bf16 v[182:185], v[98:101], v[154:157], 0
	v_mfma_f32_16x16x32_bf16 v[182:185], v[82:85], v[150:153], v[182:185]
	v_mfma_f32_16x16x32_bf16 v[134:137], v[82:85], v[158:161], 0
	v_mfma_f32_16x16x32_bf16 v[134:137], v[98:101], v[162:165], v[134:137]
	v_mfma_f32_16x16x32_bf16 v[138:141], v[78:81], v[162:165], 0
	v_mfma_f32_16x16x32_bf16 v[138:141], v[66:69], v[158:161], v[138:141]
	v_mfma_f32_16x16x32_bf16 v[114:117], v[66:69], v[170:173], 0
	v_mfma_f32_16x16x32_bf16 v[114:117], v[78:81], v[174:177], v[114:117]
	v_mfma_f32_16x16x32_bf16 v[110:113], v[98:101], v[174:177], 0
	v_mfma_f32_16x16x32_bf16 v[110:113], v[82:85], v[170:173], v[110:113]
	v_mfma_f32_16x16x32_bf16 v[86:89], v[82:85], v[178:181], 0
	v_mfma_f32_16x16x32_bf16 v[86:89], v[98:101], v[190:193], v[86:89]
	v_mfma_f32_16x16x32_bf16 v[90:93], v[78:81], v[190:193], 0
	v_mfma_f32_16x16x32_bf16 v[90:93], v[66:69], v[178:181], v[90:93]
	v_mfma_f32_16x16x32_bf16 v[166:169], v[106:109], v[150:153], 0
	v_mfma_f32_16x16x32_bf16 v[166:169], v[118:121], v[154:157], v[166:169]
	v_mfma_f32_16x16x32_bf16 v[146:149], v[142:145], v[154:157], 0
	v_mfma_f32_16x16x32_bf16 v[146:149], v[130:133], v[150:153], v[146:149]
	v_mfma_f32_16x16x32_bf16 v[122:125], v[130:133], v[158:161], 0
	v_mfma_f32_16x16x32_bf16 v[122:125], v[142:145], v[162:165], v[122:125]
	v_mfma_f32_16x16x32_bf16 v[126:129], v[118:121], v[162:165], 0
	v_mfma_f32_16x16x32_bf16 v[126:129], v[106:109], v[158:161], v[126:129]
	v_mfma_f32_16x16x32_bf16 v[102:105], v[106:109], v[170:173], 0
	v_mfma_f32_16x16x32_bf16 v[102:105], v[118:121], v[174:177], v[102:105]
	v_mfma_f32_16x16x32_bf16 v[94:97], v[142:145], v[174:177], 0
	v_mfma_f32_16x16x32_bf16 v[94:97], v[130:133], v[170:173], v[94:97]
	v_mfma_f32_16x16x32_bf16 v[70:73], v[130:133], v[178:181], 0
	v_mfma_f32_16x16x32_bf16 v[70:73], v[142:145], v[190:193], v[70:73]
	v_mfma_f32_16x16x32_bf16 v[74:77], v[118:121], v[190:193], 0
	v_mfma_f32_16x16x32_bf16 v[74:77], v[106:109], v[178:181], v[74:77]
	s_setprio 0
	s_barrier
	ds_read_b128 v[150:153], v234 offset:16384
	ds_read_b128 v[154:157], v234 offset:17408
	ds_read_b128 v[158:161], v234 offset:18432
	ds_read_b128 v[162:165], v234 offset:19456
	ds_read_b128 v[170:173], v234 offset:20480
	ds_read_b128 v[174:177], v234 offset:21504
	ds_read_b128 v[178:181], v234 offset:22528
	ds_read_b128 v[190:193], v234 offset:23552
	s_add_i32 s58, s58, s24
	v_lshl_add_u64 v[214:215], s[56:57], 0, v[194:195]
	s_mov_b32 m0, s58
	s_nop 0
	global_load_lds_dwordx4 v194, s[56:57]
	s_add_i32 m0, s58, 0x2000
	v_lshl_add_u64 v[216:217], s[56:57], 0, v[204:205]
	s_add_u32 s56, s56, s12
	s_addc_u32 s57, s57, 0
	s_add_i32 s58, s59, s24
	global_load_lds_dwordx4 v[216:217], off
	v_lshl_add_u64 v[218:219], s[56:57], 0, v[194:195]
	s_mov_b32 m0, s58
	v_lshl_add_u64 v[220:221], s[56:57], 0, v[204:205]
	global_load_lds_dwordx4 v194, s[56:57]
	s_add_i32 m0, s58, 0x2000
	s_nop 0
	global_load_lds_dwordx4 v204, s[56:57]
	s_waitcnt vmcnt(6)
	s_waitcnt lgkmcnt(0)
	v_mfma_f32_16x16x32_bf16 v[62:65], v[66:69], v[150:153], 0
	v_mfma_f32_16x16x32_bf16 v[62:65], v[78:81], v[154:157], v[62:65]
	s_barrier
	s_setprio 1
	v_mfma_f32_16x16x32_bf16 v[58:61], v[98:101], v[154:157], 0
	v_mfma_f32_16x16x32_bf16 v[58:61], v[82:85], v[150:153], v[58:61]
	v_mfma_f32_16x16x32_bf16 v[42:45], v[82:85], v[158:161], 0
	v_mfma_f32_16x16x32_bf16 v[42:45], v[98:101], v[162:165], v[42:45]
	v_mfma_f32_16x16x32_bf16 v[46:49], v[78:81], v[162:165], 0
	v_mfma_f32_16x16x32_bf16 v[46:49], v[66:69], v[158:161], v[46:49]
	v_mfma_f32_16x16x32_bf16 v[30:33], v[66:69], v[170:173], 0
	v_mfma_f32_16x16x32_bf16 v[30:33], v[78:81], v[174:177], v[30:33]
	v_mfma_f32_16x16x32_bf16 v[26:29], v[98:101], v[174:177], 0
	v_mfma_f32_16x16x32_bf16 v[26:29], v[82:85], v[170:173], v[26:29]
	v_mfma_f32_16x16x32_bf16 v[10:13], v[82:85], v[178:181], 0
	v_mfma_f32_16x16x32_bf16 v[10:13], v[98:101], v[190:193], v[10:13]
	v_mfma_f32_16x16x32_bf16 v[14:17], v[78:81], v[190:193], 0
	v_mfma_f32_16x16x32_bf16 v[14:17], v[66:69], v[178:181], v[14:17]
	v_mfma_f32_16x16x32_bf16 v[54:57], v[106:109], v[150:153], 0
	v_mfma_f32_16x16x32_bf16 v[54:57], v[118:121], v[154:157], v[54:57]
	v_mfma_f32_16x16x32_bf16 v[50:53], v[142:145], v[154:157], 0
	v_mfma_f32_16x16x32_bf16 v[50:53], v[130:133], v[150:153], v[50:53]
	v_mfma_f32_16x16x32_bf16 v[34:37], v[130:133], v[158:161], 0
	v_mfma_f32_16x16x32_bf16 v[34:37], v[142:145], v[162:165], v[34:37]
	v_mfma_f32_16x16x32_bf16 v[38:41], v[118:121], v[162:165], 0
	v_mfma_f32_16x16x32_bf16 v[38:41], v[106:109], v[158:161], v[38:41]
	v_mfma_f32_16x16x32_bf16 v[22:25], v[106:109], v[170:173], 0
	v_mfma_f32_16x16x32_bf16 v[22:25], v[118:121], v[174:177], v[22:25]
	v_mfma_f32_16x16x32_bf16 v[18:21], v[142:145], v[174:177], 0
	v_mfma_f32_16x16x32_bf16 v[18:21], v[130:133], v[170:173], v[18:21]
	v_mfma_f32_16x16x32_bf16 v[2:5], v[130:133], v[178:181], 0
	v_mfma_f32_16x16x32_bf16 v[2:5], v[142:145], v[190:193], v[2:5]
	v_mfma_f32_16x16x32_bf16 v[6:9], v[118:121], v[190:193], 0
	v_mfma_f32_16x16x32_bf16 v[6:9], v[106:109], v[178:181], v[6:9]
	s_setprio 0
	s_barrier
	s_mov_b32 m0, s26
	s_nop 0
	global_load_lds_dwordx4 v208, s[20:21]
	s_mov_b32 m0, s27
	s_nop 0
	global_load_lds_dwordx4 v206, s[20:21]
	ds_read_b128 v[66:69], v198 offset:32768
	ds_read_b128 v[78:81], v198 offset:33792
	ds_read_b128 v[82:85], v198 offset:34816
	ds_read_b128 v[98:101], v198 offset:35840
	ds_read_b128 v[106:109], v198 offset:49152
	ds_read_b128 v[118:121], v198 offset:50176
	ds_read_b128 v[130:133], v198 offset:51200
	ds_read_b128 v[142:145], v198 offset:52224
	ds_read_b128 v[150:153], v234 offset:32768
	ds_read_b128 v[154:157], v234 offset:33792
	ds_read_b128 v[158:161], v234 offset:34816
	ds_read_b128 v[162:165], v234 offset:35840
	ds_read_b128 v[170:173], v234 offset:36864
	ds_read_b128 v[174:177], v234 offset:37888
	ds_read_b128 v[178:181], v234 offset:38912
	ds_read_b128 v[190:193], v234 offset:39936
	s_add_i32 s56, 0, 0x18000
	s_add_i32 s57, 0, 0x1c000
	s_add_u32 s20, s20, s12
	s_addc_u32 s21, s21, 0
	s_mov_b32 m0, s28
	s_nop 0
	global_load_lds_dwordx4 v208, s[20:21]
	s_mov_b32 m0, s29
	s_nop 0
	global_load_lds_dwordx4 v206, s[20:21]
	s_waitcnt vmcnt(8)
	s_waitcnt lgkmcnt(0)
	v_mfma_f32_16x16x32_bf16 v[186:189], v[66:69], v[150:153], v[186:189]
	v_mfma_f32_16x16x32_bf16 v[186:189], v[78:81], v[154:157], v[186:189]
	s_barrier
	s_setprio 1
	v_mfma_f32_16x16x32_bf16 v[182:185], v[98:101], v[154:157], v[182:185]
	v_mfma_f32_16x16x32_bf16 v[182:185], v[82:85], v[150:153], v[182:185]
	v_mfma_f32_16x16x32_bf16 v[134:137], v[82:85], v[158:161], v[134:137]
	v_mfma_f32_16x16x32_bf16 v[134:137], v[98:101], v[162:165], v[134:137]
	v_mfma_f32_16x16x32_bf16 v[138:141], v[78:81], v[162:165], v[138:141]
	v_mfma_f32_16x16x32_bf16 v[138:141], v[66:69], v[158:161], v[138:141]
	v_mfma_f32_16x16x32_bf16 v[114:117], v[66:69], v[170:173], v[114:117]
	v_mfma_f32_16x16x32_bf16 v[114:117], v[78:81], v[174:177], v[114:117]
	v_mfma_f32_16x16x32_bf16 v[110:113], v[98:101], v[174:177], v[110:113]
	v_mfma_f32_16x16x32_bf16 v[110:113], v[82:85], v[170:173], v[110:113]
	v_mfma_f32_16x16x32_bf16 v[86:89], v[82:85], v[178:181], v[86:89]
	v_mfma_f32_16x16x32_bf16 v[86:89], v[98:101], v[190:193], v[86:89]
	v_mfma_f32_16x16x32_bf16 v[90:93], v[78:81], v[190:193], v[90:93]
	v_mfma_f32_16x16x32_bf16 v[90:93], v[66:69], v[178:181], v[90:93]
	v_mfma_f32_16x16x32_bf16 v[166:169], v[106:109], v[150:153], v[166:169]
	v_mfma_f32_16x16x32_bf16 v[166:169], v[118:121], v[154:157], v[166:169]
	v_mfma_f32_16x16x32_bf16 v[146:149], v[142:145], v[154:157], v[146:149]
	v_mfma_f32_16x16x32_bf16 v[146:149], v[130:133], v[150:153], v[146:149]
	v_mfma_f32_16x16x32_bf16 v[122:125], v[130:133], v[158:161], v[122:125]
	v_mfma_f32_16x16x32_bf16 v[122:125], v[142:145], v[162:165], v[122:125]
	v_mfma_f32_16x16x32_bf16 v[126:129], v[118:121], v[162:165], v[126:129]
	v_mfma_f32_16x16x32_bf16 v[126:129], v[106:109], v[158:161], v[126:129]
	v_mfma_f32_16x16x32_bf16 v[102:105], v[106:109], v[170:173], v[102:105]
	v_mfma_f32_16x16x32_bf16 v[102:105], v[118:121], v[174:177], v[102:105]
	v_mfma_f32_16x16x32_bf16 v[94:97], v[142:145], v[174:177], v[94:97]
	v_mfma_f32_16x16x32_bf16 v[94:97], v[130:133], v[170:173], v[94:97]
	v_mfma_f32_16x16x32_bf16 v[70:73], v[130:133], v[178:181], v[70:73]
	v_mfma_f32_16x16x32_bf16 v[70:73], v[142:145], v[190:193], v[70:73]
	v_mfma_f32_16x16x32_bf16 v[74:77], v[118:121], v[190:193], v[74:77]
	v_mfma_f32_16x16x32_bf16 v[74:77], v[106:109], v[178:181], v[74:77]
	s_setprio 0
	s_barrier
	ds_read_b128 v[150:153], v234 offset:49152
	ds_read_b128 v[154:157], v234 offset:50176
	ds_read_b128 v[158:161], v234 offset:51200
	ds_read_b128 v[162:165], v234 offset:52224
	ds_read_b128 v[170:173], v234 offset:53248
	ds_read_b128 v[174:177], v234 offset:54272
	ds_read_b128 v[178:181], v234 offset:55296
	ds_read_b128 v[190:193], v234 offset:56320
	s_add_i32 s20, s56, s24
	v_lshl_add_u64 v[214:215], v[214:215], 0, s[94:95]
	s_mov_b32 m0, s20
	s_nop 0
	global_load_lds_dwordx4 v[214:215], off
	v_lshl_add_u64 v[214:215], v[216:217], 0, s[94:95]
	s_add_i32 m0, s20, 0x2000
	s_add_i32 s20, s57, s24
	global_load_lds_dwordx4 v[214:215], off
	v_lshl_add_u64 v[214:215], v[218:219], 0, s[94:95]
	s_mov_b32 m0, s20
	s_nop 0
	global_load_lds_dwordx4 v[214:215], off
	v_lshl_add_u64 v[214:215], v[220:221], 0, s[94:95]
	s_add_i32 m0, s20, 0x2000
	s_nop 0
	global_load_lds_dwordx4 v[214:215], off
	s_waitcnt vmcnt(6)
	s_waitcnt lgkmcnt(0)
	v_mfma_f32_16x16x32_bf16 v[62:65], v[66:69], v[150:153], v[62:65]
	v_mfma_f32_16x16x32_bf16 v[62:65], v[78:81], v[154:157], v[62:65]
	s_barrier
	s_setprio 1
	v_mfma_f32_16x16x32_bf16 v[58:61], v[98:101], v[154:157], v[58:61]
	v_mfma_f32_16x16x32_bf16 v[58:61], v[82:85], v[150:153], v[58:61]
	v_mfma_f32_16x16x32_bf16 v[42:45], v[82:85], v[158:161], v[42:45]
	v_mfma_f32_16x16x32_bf16 v[42:45], v[98:101], v[162:165], v[42:45]
	v_mfma_f32_16x16x32_bf16 v[46:49], v[78:81], v[162:165], v[46:49]
	v_mfma_f32_16x16x32_bf16 v[46:49], v[66:69], v[158:161], v[46:49]
	v_mfma_f32_16x16x32_bf16 v[30:33], v[66:69], v[170:173], v[30:33]
	v_mfma_f32_16x16x32_bf16 v[30:33], v[78:81], v[174:177], v[30:33]
	v_mfma_f32_16x16x32_bf16 v[26:29], v[98:101], v[174:177], v[26:29]
	v_mfma_f32_16x16x32_bf16 v[26:29], v[82:85], v[170:173], v[26:29]
	v_mfma_f32_16x16x32_bf16 v[10:13], v[82:85], v[178:181], v[10:13]
	v_mfma_f32_16x16x32_bf16 v[10:13], v[98:101], v[190:193], v[10:13]
	s_add_u32 s18, s18, 0x100
	v_mfma_f32_16x16x32_bf16 v[14:17], v[78:81], v[190:193], v[14:17]
	v_mfma_f32_16x16x32_bf16 v[14:17], v[66:69], v[178:181], v[14:17]
	s_addc_u32 s19, s19, 0
	v_mfma_f32_16x16x32_bf16 v[54:57], v[106:109], v[150:153], v[54:57]
	v_mfma_f32_16x16x32_bf16 v[54:57], v[118:121], v[154:157], v[54:57]
	s_add_u32 s51, s51, 0x100
	v_mfma_f32_16x16x32_bf16 v[50:53], v[142:145], v[154:157], v[50:53]
	v_mfma_f32_16x16x32_bf16 v[50:53], v[130:133], v[150:153], v[50:53]
	s_addc_u32 s54, s54, 0
	v_mfma_f32_16x16x32_bf16 v[34:37], v[130:133], v[158:161], v[34:37]
	v_mfma_f32_16x16x32_bf16 v[34:37], v[142:145], v[162:165], v[34:37]
	s_cmp_ge_u32 s55, s53
	v_mfma_f32_16x16x32_bf16 v[38:41], v[118:121], v[162:165], v[38:41]
	v_mfma_f32_16x16x32_bf16 v[38:41], v[106:109], v[158:161], v[38:41]
	s_mov_b32 s20, s55
	v_mfma_f32_16x16x32_bf16 v[22:25], v[106:109], v[170:173], v[22:25]
	v_mfma_f32_16x16x32_bf16 v[22:25], v[118:121], v[174:177], v[22:25]
	v_mfma_f32_16x16x32_bf16 v[18:21], v[142:145], v[174:177], v[18:21]
	v_mfma_f32_16x16x32_bf16 v[18:21], v[130:133], v[170:173], v[18:21]
	v_mfma_f32_16x16x32_bf16 v[2:5], v[130:133], v[178:181], v[2:5]
	v_mfma_f32_16x16x32_bf16 v[2:5], v[142:145], v[190:193], v[2:5]
	v_mfma_f32_16x16x32_bf16 v[6:9], v[118:121], v[190:193], v[6:9]
	v_mfma_f32_16x16x32_bf16 v[6:9], v[106:109], v[178:181], v[6:9]
	s_setprio 0
	s_barrier
	s_cbranch_scc1 .Lpeel_exit_5

.Lpeel_exit_5:
	s_add_u32 vcc_lo, s0, 0x80
	s_addc_u32 vcc_hi, s1, 0
	s_sub_u32 vcc_lo, vcc_lo, s12
	s_subb_u32 vcc_hi, vcc_hi, 0
	s_mov_b32 m0, s33
	s_nop 0
	global_load_lds_dwordx4 v210, vcc
	s_mov_b32 m0, s34
	s_nop 0
	global_load_lds_dwordx4 v212, vcc
	s_add_u32 vcc_lo, s0, 0x80
	s_addc_u32 vcc_hi, s1, 0
	s_add_i32 m0, s26, 0xc000
	s_nop 0
	global_load_lds_dwordx4 v210, vcc
	s_add_i32 m0, s26, 0xe000
	s_nop 0
	global_load_lds_dwordx4 v212, vcc

.LBB0_972:
	s_ashr_i32 s29, s28, 31
	s_lshl_b64 s[10:11], s[28:29], 20
	s_add_u32 s36, s46, s10
	s_addc_u32 s37, s47, s11
	s_and_b64 s[4:5], s[4:5], exec
	s_cselect_b32 s13, s37, s7
	s_cselect_b32 s29, s36, s6
	s_add_u32 s33, s6, 0x100
	s_addc_u32 s38, s7, 0
	s_mov_b32 s39, -2
	ds_read_b128 v[130:133], v246
	ds_read_b128 v[134:137], v246 offset:1024
	ds_read_b128 v[150:153], v246 offset:2048
	ds_read_b128 v[154:157], v246 offset:3072
	ds_read_b128 v[158:161], v246 offset:16384
	ds_read_b128 v[162:165], v246 offset:17408
	ds_read_b128 v[166:169], v246 offset:18432
	ds_read_b128 v[170:173], v246 offset:19456
	ds_read_b128 v[174:177], v247
	ds_read_b128 v[178:181], v247 offset:1024
	ds_read_b128 v[182:185], v247 offset:2048
	ds_read_b128 v[186:189], v247 offset:3072
	ds_read_b128 v[190:193], v247 offset:4096
	ds_read_b128 v[204:207], v247 offset:5120
	ds_read_b128 v[208:211], v247 offset:6144
	ds_read_b128 v[212:215], v247 offset:7168
	s_add_u32 s4, s0, 0x100
	s_addc_u32 s5, s1, 0
	s_add_i32 s40, 0, 0x10000
	s_cmp_eq_u32 s39, 28
	s_cselect_b32 s11, s35, s5
	s_cselect_b32 s10, s34, s4
	s_cselect_b32 s7, s13, s38
	s_cselect_b32 s6, s29, s33
	s_add_i32 s41, 0, 0x14000
	s_cmp_eq_u32 s9, 0
	s_cbranch_scc0 .Lpeel_skipA_7
	s_add_u32 vcc_lo, s0, 0xffffc000
	s_addc_u32 vcc_hi, s1, -1
	s_mov_b32 m0, s59
	s_nop 0
	global_load_lds_dwordx4 v146, vcc
	s_mov_b32 m0, s60
	s_nop 0
	global_load_lds_dwordx4 v148, vcc
	s_add_i32 m0, s49, 0xc000
	s_nop 0
	global_load_lds_dwordx4 v146, s[0:1]
	s_add_i32 m0, s49, 0xe000
	s_nop 0
	global_load_lds_dwordx4 v148, s[0:1]
.Lpeel_skipA_7:
	s_waitcnt vmcnt(16)
	s_waitcnt lgkmcnt(0)
	v_mfma_f32_16x16x32_bf16 v[126:129], v[130:133], v[174:177], 0
	v_mfma_f32_16x16x32_bf16 v[126:129], v[134:137], v[178:181], v[126:129]
	s_barrier
	s_setprio 1
	v_mfma_f32_16x16x32_bf16 v[62:65], v[154:157], v[178:181], 0
	v_mfma_f32_16x16x32_bf16 v[62:65], v[150:153], v[174:177], v[62:65]
	v_mfma_f32_16x16x32_bf16 v[58:61], v[150:153], v[182:185], 0
	v_mfma_f32_16x16x32_bf16 v[58:61], v[154:157], v[186:189], v[58:61]
	v_mfma_f32_16x16x32_bf16 v[122:125], v[134:137], v[186:189], 0
	v_mfma_f32_16x16x32_bf16 v[122:125], v[130:133], v[182:185], v[122:125]
	v_mfma_f32_16x16x32_bf16 v[114:117], v[130:133], v[190:193], 0
	v_mfma_f32_16x16x32_bf16 v[114:117], v[134:137], v[204:207], v[114:117]
	v_mfma_f32_16x16x32_bf16 v[50:53], v[154:157], v[204:207], 0
	v_mfma_f32_16x16x32_bf16 v[50:53], v[150:153], v[190:193], v[50:53]
	v_mfma_f32_16x16x32_bf16 v[42:45], v[150:153], v[208:211], 0
	v_mfma_f32_16x16x32_bf16 v[42:45], v[154:157], v[212:215], v[42:45]
	v_mfma_f32_16x16x32_bf16 v[106:109], v[134:137], v[212:215], 0
	v_mfma_f32_16x16x32_bf16 v[106:109], v[130:133], v[208:211], v[106:109]
	v_mfma_f32_16x16x32_bf16 v[118:121], v[158:161], v[174:177], 0
	v_mfma_f32_16x16x32_bf16 v[118:121], v[162:165], v[178:181], v[118:121]
	v_mfma_f32_16x16x32_bf16 v[54:57], v[170:173], v[178:181], 0
	v_mfma_f32_16x16x32_bf16 v[54:57], v[166:169], v[174:177], v[54:57]
	v_mfma_f32_16x16x32_bf16 v[46:49], v[166:169], v[182:185], 0
	v_mfma_f32_16x16x32_bf16 v[46:49], v[170:173], v[186:189], v[46:49]
	v_mfma_f32_16x16x32_bf16 v[110:113], v[162:165], v[186:189], 0
	v_mfma_f32_16x16x32_bf16 v[110:113], v[158:161], v[182:185], v[110:113]
	v_mfma_f32_16x16x32_bf16 v[102:105], v[158:161], v[190:193], 0
	v_mfma_f32_16x16x32_bf16 v[102:105], v[162:165], v[204:207], v[102:105]
	v_mfma_f32_16x16x32_bf16 v[38:41], v[170:173], v[204:207], 0
	v_mfma_f32_16x16x32_bf16 v[38:41], v[166:169], v[190:193], v[38:41]
	v_mfma_f32_16x16x32_bf16 v[34:37], v[166:169], v[208:211], 0
	v_mfma_f32_16x16x32_bf16 v[34:37], v[170:173], v[212:215], v[34:37]
	v_mfma_f32_16x16x32_bf16 v[98:101], v[162:165], v[212:215], 0
	v_mfma_f32_16x16x32_bf16 v[98:101], v[158:161], v[208:211], v[98:101]
	s_setprio 0
	s_barrier
	ds_read_b128 v[174:177], v247 offset:16384
	ds_read_b128 v[178:181], v247 offset:17408
	ds_read_b128 v[182:185], v247 offset:18432
	ds_read_b128 v[186:189], v247 offset:19456
	ds_read_b128 v[190:193], v247 offset:20480
	ds_read_b128 v[204:207], v247 offset:21504
	ds_read_b128 v[208:211], v247 offset:22528
	ds_read_b128 v[212:215], v247 offset:23552
	s_add_i32 s0, s40, s48
	s_mov_b32 m0, s0
	s_nop 0
	global_load_lds_dwordx4 v140, s[6:7]
	s_add_i32 m0, s0, 0x2000
	s_add_u32 s0, s6, 0x80000
	s_addc_u32 s1, s7, 0
	s_add_i32 s40, s41, s48
	global_load_lds_dwordx4 v144, s[6:7]
	s_mov_b32 m0, s40
	s_nop 0
	global_load_lds_dwordx4 v140, s[0:1]
	s_add_i32 m0, s40, 0x2000
	s_nop 0
	global_load_lds_dwordx4 v144, s[0:1]
	s_waitcnt vmcnt(6)
	s_waitcnt lgkmcnt(0)
	v_mfma_f32_16x16x32_bf16 v[94:97], v[130:133], v[174:177], 0
	v_mfma_f32_16x16x32_bf16 v[94:97], v[134:137], v[178:181], v[94:97]
	s_barrier
	s_setprio 1
	v_mfma_f32_16x16x32_bf16 v[30:33], v[154:157], v[178:181], 0
	v_mfma_f32_16x16x32_bf16 v[30:33], v[150:153], v[174:177], v[30:33]
	v_mfma_f32_16x16x32_bf16 v[26:29], v[150:153], v[182:185], 0
	v_mfma_f32_16x16x32_bf16 v[26:29], v[154:157], v[186:189], v[26:29]
	v_mfma_f32_16x16x32_bf16 v[90:93], v[134:137], v[186:189], 0
	v_mfma_f32_16x16x32_bf16 v[90:93], v[130:133], v[182:185], v[90:93]
	v_mfma_f32_16x16x32_bf16 v[82:85], v[130:133], v[190:193], 0
	v_mfma_f32_16x16x32_bf16 v[82:85], v[134:137], v[204:207], v[82:85]
	v_mfma_f32_16x16x32_bf16 v[18:21], v[154:157], v[204:207], 0
	v_mfma_f32_16x16x32_bf16 v[18:21], v[150:153], v[190:193], v[18:21]
	v_mfma_f32_16x16x32_bf16 v[10:13], v[150:153], v[208:211], 0
	v_mfma_f32_16x16x32_bf16 v[10:13], v[154:157], v[212:215], v[10:13]
	v_mfma_f32_16x16x32_bf16 v[74:77], v[134:137], v[212:215], 0
	v_mfma_f32_16x16x32_bf16 v[74:77], v[130:133], v[208:211], v[74:77]
	v_mfma_f32_16x16x32_bf16 v[86:89], v[158:161], v[174:177], 0
	v_mfma_f32_16x16x32_bf16 v[86:89], v[162:165], v[178:181], v[86:89]
	v_mfma_f32_16x16x32_bf16 v[22:25], v[170:173], v[178:181], 0
	v_mfma_f32_16x16x32_bf16 v[22:25], v[166:169], v[174:177], v[22:25]
	v_mfma_f32_16x16x32_bf16 v[14:17], v[166:169], v[182:185], 0
	v_mfma_f32_16x16x32_bf16 v[14:17], v[170:173], v[186:189], v[14:17]
	v_mfma_f32_16x16x32_bf16 v[78:81], v[162:165], v[186:189], 0
	v_mfma_f32_16x16x32_bf16 v[78:81], v[158:161], v[182:185], v[78:81]
	v_mfma_f32_16x16x32_bf16 v[70:73], v[158:161], v[190:193], 0
	v_mfma_f32_16x16x32_bf16 v[70:73], v[162:165], v[204:207], v[70:73]
	v_mfma_f32_16x16x32_bf16 v[6:9], v[170:173], v[204:207], 0
	v_mfma_f32_16x16x32_bf16 v[6:9], v[166:169], v[190:193], v[6:9]
	v_mfma_f32_16x16x32_bf16 v[2:5], v[166:169], v[208:211], 0
	v_mfma_f32_16x16x32_bf16 v[2:5], v[170:173], v[212:215], v[2:5]
	v_mfma_f32_16x16x32_bf16 v[66:69], v[162:165], v[212:215], 0
	v_mfma_f32_16x16x32_bf16 v[66:69], v[158:161], v[208:211], v[66:69]
	s_setprio 0
	s_barrier
	s_mov_b32 m0, s49
	s_nop 0
	global_load_lds_dwordx4 v138, s[10:11]
	s_mov_b32 m0, s70
	s_nop 0
	global_load_lds_dwordx4 v142, s[10:11]
	ds_read_b128 v[130:133], v246 offset:32768
	ds_read_b128 v[134:137], v246 offset:33792
	ds_read_b128 v[150:153], v246 offset:34816
	ds_read_b128 v[154:157], v246 offset:35840
	ds_read_b128 v[158:161], v246 offset:49152
	ds_read_b128 v[162:165], v246 offset:50176
	ds_read_b128 v[166:169], v246 offset:51200
	ds_read_b128 v[170:173], v246 offset:52224
	ds_read_b128 v[174:177], v247 offset:32768
	ds_read_b128 v[178:181], v247 offset:33792
	ds_read_b128 v[182:185], v247 offset:34816
	ds_read_b128 v[186:189], v247 offset:35840
	ds_read_b128 v[190:193], v247 offset:36864
	ds_read_b128 v[204:207], v247 offset:37888
	ds_read_b128 v[208:211], v247 offset:38912
	ds_read_b128 v[212:215], v247 offset:39936
	s_add_i32 s40, 0, 0x18000
	s_add_i32 s41, 0, 0x1c000
	s_add_u32 s0, s10, 0x4000
	s_addc_u32 s1, s11, 0
	s_mov_b32 m0, s71
	s_nop 0
	global_load_lds_dwordx4 v138, s[0:1]
	s_mov_b32 m0, s73
	s_nop 0
	global_load_lds_dwordx4 v142, s[0:1]
	s_waitcnt vmcnt(8)
	s_waitcnt lgkmcnt(0)
	v_mfma_f32_16x16x32_bf16 v[126:129], v[130:133], v[174:177], v[126:129]
	v_mfma_f32_16x16x32_bf16 v[126:129], v[134:137], v[178:181], v[126:129]
	s_barrier
	s_setprio 1
	v_mfma_f32_16x16x32_bf16 v[62:65], v[154:157], v[178:181], v[62:65]
	v_mfma_f32_16x16x32_bf16 v[62:65], v[150:153], v[174:177], v[62:65]
	v_mfma_f32_16x16x32_bf16 v[58:61], v[150:153], v[182:185], v[58:61]
	v_mfma_f32_16x16x32_bf16 v[58:61], v[154:157], v[186:189], v[58:61]
	v_mfma_f32_16x16x32_bf16 v[122:125], v[134:137], v[186:189], v[122:125]
	v_mfma_f32_16x16x32_bf16 v[122:125], v[130:133], v[182:185], v[122:125]
	v_mfma_f32_16x16x32_bf16 v[114:117], v[130:133], v[190:193], v[114:117]
	v_mfma_f32_16x16x32_bf16 v[114:117], v[134:137], v[204:207], v[114:117]
	v_mfma_f32_16x16x32_bf16 v[50:53], v[154:157], v[204:207], v[50:53]
	v_mfma_f32_16x16x32_bf16 v[50:53], v[150:153], v[190:193], v[50:53]
	v_mfma_f32_16x16x32_bf16 v[42:45], v[150:153], v[208:211], v[42:45]
	v_mfma_f32_16x16x32_bf16 v[42:45], v[154:157], v[212:215], v[42:45]
	v_mfma_f32_16x16x32_bf16 v[106:109], v[134:137], v[212:215], v[106:109]
	v_mfma_f32_16x16x32_bf16 v[106:109], v[130:133], v[208:211], v[106:109]
	v_mfma_f32_16x16x32_bf16 v[118:121], v[158:161], v[174:177], v[118:121]
	v_mfma_f32_16x16x32_bf16 v[118:121], v[162:165], v[178:181], v[118:121]
	v_mfma_f32_16x16x32_bf16 v[54:57], v[170:173], v[178:181], v[54:57]
	v_mfma_f32_16x16x32_bf16 v[54:57], v[166:169], v[174:177], v[54:57]
	v_mfma_f32_16x16x32_bf16 v[46:49], v[166:169], v[182:185], v[46:49]
	v_mfma_f32_16x16x32_bf16 v[46:49], v[170:173], v[186:189], v[46:49]
	v_mfma_f32_16x16x32_bf16 v[110:113], v[162:165], v[186:189], v[110:113]
	v_mfma_f32_16x16x32_bf16 v[110:113], v[158:161], v[182:185], v[110:113]
	v_mfma_f32_16x16x32_bf16 v[102:105], v[158:161], v[190:193], v[102:105]
	v_mfma_f32_16x16x32_bf16 v[102:105], v[162:165], v[204:207], v[102:105]
	v_mfma_f32_16x16x32_bf16 v[38:41], v[170:173], v[204:207], v[38:41]
	v_mfma_f32_16x16x32_bf16 v[38:41], v[166:169], v[190:193], v[38:41]
	v_mfma_f32_16x16x32_bf16 v[34:37], v[166:169], v[208:211], v[34:37]
	v_mfma_f32_16x16x32_bf16 v[34:37], v[170:173], v[212:215], v[34:37]
	v_mfma_f32_16x16x32_bf16 v[98:101], v[162:165], v[212:215], v[98:101]
	v_mfma_f32_16x16x32_bf16 v[98:101], v[158:161], v[208:211], v[98:101]
	s_setprio 0
	s_barrier
	ds_read_b128 v[174:177], v247 offset:49152
	ds_read_b128 v[178:181], v247 offset:50176
	ds_read_b128 v[182:185], v247 offset:51200
	ds_read_b128 v[186:189], v247 offset:52224
	ds_read_b128 v[190:193], v247 offset:53248
	ds_read_b128 v[204:207], v247 offset:54272
	ds_read_b128 v[208:211], v247 offset:55296
	ds_read_b128 v[212:215], v247 offset:56320
	s_add_i32 s0, s40, s48
	s_add_u32 vcc_lo, s6, s94
	s_addc_u32 vcc_hi, s7, s95
	s_mov_b32 m0, s0
	s_nop 0
	global_load_lds_dwordx4 v140, vcc
	s_add_i32 m0, s0, 0x2000
	s_add_u32 s0, s6, 0x80080
	s_addc_u32 s1, s7, 0
	s_add_i32 s6, s41, s48
	global_load_lds_dwordx4 v144, vcc
	s_mov_b32 m0, s6
	s_nop 0
	global_load_lds_dwordx4 v140, s[0:1]
	s_add_i32 m0, s6, 0x2000
	s_nop 0
	global_load_lds_dwordx4 v144, s[0:1]
	s_waitcnt vmcnt(6)
	s_waitcnt lgkmcnt(0)
	v_mfma_f32_16x16x32_bf16 v[94:97], v[130:133], v[174:177], v[94:97]
	v_mfma_f32_16x16x32_bf16 v[94:97], v[134:137], v[178:181], v[94:97]
	s_barrier
	s_setprio 1
	v_mfma_f32_16x16x32_bf16 v[30:33], v[154:157], v[178:181], v[30:33]
	v_mfma_f32_16x16x32_bf16 v[30:33], v[150:153], v[174:177], v[30:33]
	v_mfma_f32_16x16x32_bf16 v[26:29], v[150:153], v[182:185], v[26:29]
	v_mfma_f32_16x16x32_bf16 v[26:29], v[154:157], v[186:189], v[26:29]
	v_mfma_f32_16x16x32_bf16 v[90:93], v[134:137], v[186:189], v[90:93]
	v_mfma_f32_16x16x32_bf16 v[90:93], v[130:133], v[182:185], v[90:93]
	v_mfma_f32_16x16x32_bf16 v[82:85], v[130:133], v[190:193], v[82:85]
	v_mfma_f32_16x16x32_bf16 v[82:85], v[134:137], v[204:207], v[82:85]
	v_mfma_f32_16x16x32_bf16 v[18:21], v[154:157], v[204:207], v[18:21]
	v_mfma_f32_16x16x32_bf16 v[18:21], v[150:153], v[190:193], v[18:21]
	v_mfma_f32_16x16x32_bf16 v[10:13], v[150:153], v[208:211], v[10:13]
	v_mfma_f32_16x16x32_bf16 v[10:13], v[154:157], v[212:215], v[10:13]
	s_add_i32 s39, s39, 2
	v_mfma_f32_16x16x32_bf16 v[74:77], v[134:137], v[212:215], v[74:77]
	v_mfma_f32_16x16x32_bf16 v[74:77], v[130:133], v[208:211], v[74:77]
	s_add_u32 s33, s33, 0x100
	v_mfma_f32_16x16x32_bf16 v[86:89], v[158:161], v[174:177], v[86:89]
	v_mfma_f32_16x16x32_bf16 v[86:89], v[162:165], v[178:181], v[86:89]
	s_addc_u32 s38, s38, 0
	v_mfma_f32_16x16x32_bf16 v[22:25], v[170:173], v[178:181], v[22:25]
	v_mfma_f32_16x16x32_bf16 v[22:25], v[166:169], v[174:177], v[22:25]
	s_cmp_gt_u32 s39, 29
	v_mfma_f32_16x16x32_bf16 v[14:17], v[166:169], v[182:185], v[14:17]
	v_mfma_f32_16x16x32_bf16 v[14:17], v[170:173], v[186:189], v[14:17]
	s_mov_b64 s[0:1], s[4:5]
	v_mfma_f32_16x16x32_bf16 v[78:81], v[162:165], v[186:189], v[78:81]
	v_mfma_f32_16x16x32_bf16 v[78:81], v[158:161], v[182:185], v[78:81]
	v_mfma_f32_16x16x32_bf16 v[70:73], v[158:161], v[190:193], v[70:73]
	v_mfma_f32_16x16x32_bf16 v[70:73], v[162:165], v[204:207], v[70:73]
	v_mfma_f32_16x16x32_bf16 v[6:9], v[170:173], v[204:207], v[6:9]
	v_mfma_f32_16x16x32_bf16 v[6:9], v[166:169], v[190:193], v[6:9]
	v_mfma_f32_16x16x32_bf16 v[2:5], v[166:169], v[208:211], v[2:5]
	v_mfma_f32_16x16x32_bf16 v[2:5], v[170:173], v[212:215], v[2:5]
	v_mfma_f32_16x16x32_bf16 v[66:69], v[162:165], v[212:215], v[66:69]
	v_mfma_f32_16x16x32_bf16 v[66:69], v[158:161], v[208:211], v[66:69]
	s_setprio 0
	s_barrier
	s_cbranch_scc1 .Lpeel_exit_7

.Lpeel_exit_7:
	s_add_u32 vcc_lo, s34, 0xffffc000
	s_addc_u32 vcc_hi, s35, -1
	s_mov_b32 m0, s59
	s_nop 0
	global_load_lds_dwordx4 v146, vcc
	s_mov_b32 m0, s60
	s_nop 0
	global_load_lds_dwordx4 v148, vcc
	s_add_i32 m0, s49, 0xc000
	s_nop 0
	global_load_lds_dwordx4 v146, s[34:35]
	s_add_i32 m0, s49, 0xe000
	s_nop 0
	global_load_lds_dwordx4 v148, s[34:35]

.LBB0_1440:
	s_add_u32 s46, s20, 0x100
	s_waitcnt lgkmcnt(0)
	s_addc_u32 s47, s21, 0
	s_mov_b32 s48, -2
	ds_read_b128 v[66:69], v198
	ds_read_b128 v[78:81], v198 offset:1024
	ds_read_b128 v[86:89], v198 offset:2048
	ds_read_b128 v[98:101], v198 offset:3072
	ds_read_b128 v[106:109], v198 offset:16384
	ds_read_b128 v[118:121], v198 offset:17408
	ds_read_b128 v[130:133], v198 offset:18432
	ds_read_b128 v[142:145], v198 offset:19456
	ds_read_b128 v[150:153], v234
	ds_read_b128 v[154:157], v234 offset:1024
	ds_read_b128 v[158:161], v234 offset:2048
	ds_read_b128 v[162:165], v234 offset:3072
	ds_read_b128 v[170:173], v234 offset:4096
	ds_read_b128 v[174:177], v234 offset:5120
	ds_read_b128 v[178:181], v234 offset:6144
	ds_read_b128 v[190:193], v234 offset:7168
	s_add_u32 s20, s18, 0x100
	s_addc_u32 s21, s19, 0
	s_add_i32 s49, 0, 0x10000
	s_cmpk_eq_i32 s48, 0x54
	s_cselect_b32 s25, s1, s21
	s_cselect_b32 s24, s0, s20
	s_cselect_b32 s23, s17, s47
	s_cselect_b32 s22, s16, s46
	s_add_i32 s50, 0, 0x14000
	s_cmp_eq_u32 s41, 1
	s_cbranch_scc0 .Lpeel_skipA_8
	s_add_u32 vcc_lo, s18, 0xffea0000
	s_addc_u32 vcc_hi, s19, -1
	s_mov_b32 m0, s38
	s_nop 0
	global_load_lds_dwordx4 v210, vcc
	s_mov_b32 m0, s40
	s_nop 0
	global_load_lds_dwordx4 v212, vcc
	s_add_i32 m0, s28, 0xc000
	s_nop 0
	global_load_lds_dwordx4 v210, s[18:19]
	s_add_i32 m0, s28, 0xe000
	s_nop 0
	global_load_lds_dwordx4 v212, s[18:19]
.Lpeel_skipA_8:
	s_waitcnt vmcnt(28)
	s_waitcnt lgkmcnt(0)
	v_mfma_f32_16x16x32_bf16 v[186:189], v[66:69], v[150:153], 0
	v_mfma_f32_16x16x32_bf16 v[186:189], v[78:81], v[154:157], v[186:189]
	s_barrier
	s_setprio 1
	v_mfma_f32_16x16x32_bf16 v[182:185], v[98:101], v[154:157], 0
	v_mfma_f32_16x16x32_bf16 v[182:185], v[86:89], v[150:153], v[182:185]
	v_mfma_f32_16x16x32_bf16 v[134:137], v[86:89], v[158:161], 0
	v_mfma_f32_16x16x32_bf16 v[134:137], v[98:101], v[162:165], v[134:137]
	v_mfma_f32_16x16x32_bf16 v[138:141], v[78:81], v[162:165], 0
	v_mfma_f32_16x16x32_bf16 v[138:141], v[66:69], v[158:161], v[138:141]
	v_mfma_f32_16x16x32_bf16 v[114:117], v[66:69], v[170:173], 0
	v_mfma_f32_16x16x32_bf16 v[114:117], v[78:81], v[174:177], v[114:117]
	v_mfma_f32_16x16x32_bf16 v[110:113], v[98:101], v[174:177], 0
	v_mfma_f32_16x16x32_bf16 v[110:113], v[86:89], v[170:173], v[110:113]
	v_mfma_f32_16x16x32_bf16 v[82:85], v[86:89], v[178:181], 0
	v_mfma_f32_16x16x32_bf16 v[82:85], v[98:101], v[190:193], v[82:85]
	v_mfma_f32_16x16x32_bf16 v[90:93], v[78:81], v[190:193], 0
	v_mfma_f32_16x16x32_bf16 v[90:93], v[66:69], v[178:181], v[90:93]
	v_mfma_f32_16x16x32_bf16 v[166:169], v[106:109], v[150:153], 0
	v_mfma_f32_16x16x32_bf16 v[166:169], v[118:121], v[154:157], v[166:169]
	v_mfma_f32_16x16x32_bf16 v[146:149], v[142:145], v[154:157], 0
	v_mfma_f32_16x16x32_bf16 v[146:149], v[130:133], v[150:153], v[146:149]
	v_mfma_f32_16x16x32_bf16 v[122:125], v[130:133], v[158:161], 0
	v_mfma_f32_16x16x32_bf16 v[122:125], v[142:145], v[162:165], v[122:125]
	v_mfma_f32_16x16x32_bf16 v[126:129], v[118:121], v[162:165], 0
	v_mfma_f32_16x16x32_bf16 v[126:129], v[106:109], v[158:161], v[126:129]
	v_mfma_f32_16x16x32_bf16 v[102:105], v[106:109], v[170:173], 0
	v_mfma_f32_16x16x32_bf16 v[102:105], v[118:121], v[174:177], v[102:105]
	v_mfma_f32_16x16x32_bf16 v[94:97], v[142:145], v[174:177], 0
	v_mfma_f32_16x16x32_bf16 v[94:97], v[130:133], v[170:173], v[94:97]
	v_mfma_f32_16x16x32_bf16 v[70:73], v[130:133], v[178:181], 0
	v_mfma_f32_16x16x32_bf16 v[70:73], v[142:145], v[190:193], v[70:73]
	v_mfma_f32_16x16x32_bf16 v[74:77], v[118:121], v[190:193], 0
	v_mfma_f32_16x16x32_bf16 v[74:77], v[106:109], v[178:181], v[74:77]
	s_setprio 0
	s_barrier
	ds_read_b128 v[150:153], v234 offset:16384
	ds_read_b128 v[154:157], v234 offset:17408
	ds_read_b128 v[158:161], v234 offset:18432
	ds_read_b128 v[162:165], v234 offset:19456
	ds_read_b128 v[170:173], v234 offset:20480
	ds_read_b128 v[174:177], v234 offset:21504
	ds_read_b128 v[178:181], v234 offset:22528
	ds_read_b128 v[190:193], v234 offset:23552
	s_add_i32 s18, s49, s26
	s_mov_b32 m0, s18
	s_nop 0
	global_load_lds_dwordx4 v194, s[22:23]
	s_add_i32 m0, s18, 0x2000
	s_add_u32 s18, s22, 0x160000
	s_addc_u32 s19, s23, 0
	s_add_i32 s49, s50, s26
	global_load_lds_dwordx4 v204, s[22:23]
	s_mov_b32 m0, s49
	s_nop 0
	global_load_lds_dwordx4 v194, s[18:19]
	s_add_i32 m0, s49, 0x2000
	s_nop 0
	global_load_lds_dwordx4 v204, s[18:19]
	s_waitcnt vmcnt(6)
	s_waitcnt lgkmcnt(0)
	v_mfma_f32_16x16x32_bf16 v[62:65], v[66:69], v[150:153], 0
	v_mfma_f32_16x16x32_bf16 v[62:65], v[78:81], v[154:157], v[62:65]
	s_barrier
	s_setprio 1
	v_mfma_f32_16x16x32_bf16 v[58:61], v[98:101], v[154:157], 0
	v_mfma_f32_16x16x32_bf16 v[58:61], v[86:89], v[150:153], v[58:61]
	v_mfma_f32_16x16x32_bf16 v[42:45], v[86:89], v[158:161], 0
	v_mfma_f32_16x16x32_bf16 v[42:45], v[98:101], v[162:165], v[42:45]
	v_mfma_f32_16x16x32_bf16 v[46:49], v[78:81], v[162:165], 0
	v_mfma_f32_16x16x32_bf16 v[46:49], v[66:69], v[158:161], v[46:49]
	v_mfma_f32_16x16x32_bf16 v[30:33], v[66:69], v[170:173], 0
	v_mfma_f32_16x16x32_bf16 v[30:33], v[78:81], v[174:177], v[30:33]
	v_mfma_f32_16x16x32_bf16 v[26:29], v[98:101], v[174:177], 0
	v_mfma_f32_16x16x32_bf16 v[26:29], v[86:89], v[170:173], v[26:29]
	v_mfma_f32_16x16x32_bf16 v[10:13], v[86:89], v[178:181], 0
	v_mfma_f32_16x16x32_bf16 v[10:13], v[98:101], v[190:193], v[10:13]
	v_mfma_f32_16x16x32_bf16 v[14:17], v[78:81], v[190:193], 0
	v_mfma_f32_16x16x32_bf16 v[14:17], v[66:69], v[178:181], v[14:17]
	v_mfma_f32_16x16x32_bf16 v[54:57], v[106:109], v[150:153], 0
	v_mfma_f32_16x16x32_bf16 v[54:57], v[118:121], v[154:157], v[54:57]
	v_mfma_f32_16x16x32_bf16 v[50:53], v[142:145], v[154:157], 0
	v_mfma_f32_16x16x32_bf16 v[50:53], v[130:133], v[150:153], v[50:53]
	v_mfma_f32_16x16x32_bf16 v[34:37], v[130:133], v[158:161], 0
	v_mfma_f32_16x16x32_bf16 v[34:37], v[142:145], v[162:165], v[34:37]
	v_mfma_f32_16x16x32_bf16 v[38:41], v[118:121], v[162:165], 0
	v_mfma_f32_16x16x32_bf16 v[38:41], v[106:109], v[158:161], v[38:41]
	v_mfma_f32_16x16x32_bf16 v[22:25], v[106:109], v[170:173], 0
	v_mfma_f32_16x16x32_bf16 v[22:25], v[118:121], v[174:177], v[22:25]
	v_mfma_f32_16x16x32_bf16 v[18:21], v[142:145], v[174:177], 0
	v_mfma_f32_16x16x32_bf16 v[18:21], v[130:133], v[170:173], v[18:21]
	v_mfma_f32_16x16x32_bf16 v[2:5], v[130:133], v[178:181], 0
	v_mfma_f32_16x16x32_bf16 v[2:5], v[142:145], v[190:193], v[2:5]
	v_mfma_f32_16x16x32_bf16 v[6:9], v[118:121], v[190:193], 0
	v_mfma_f32_16x16x32_bf16 v[6:9], v[106:109], v[178:181], v[6:9]
	s_setprio 0
	s_barrier
	s_mov_b32 m0, s28
	s_nop 0
	global_load_lds_dwordx4 v208, s[24:25]
	s_mov_b32 m0, s29
	s_nop 0
	global_load_lds_dwordx4 v206, s[24:25]
	ds_read_b128 v[66:69], v198 offset:32768
	ds_read_b128 v[78:81], v198 offset:33792
	ds_read_b128 v[86:89], v198 offset:34816
	ds_read_b128 v[98:101], v198 offset:35840
	ds_read_b128 v[106:109], v198 offset:49152
	ds_read_b128 v[118:121], v198 offset:50176
	ds_read_b128 v[130:133], v198 offset:51200
	ds_read_b128 v[142:145], v198 offset:52224
	ds_read_b128 v[150:153], v234 offset:32768
	ds_read_b128 v[154:157], v234 offset:33792
	ds_read_b128 v[158:161], v234 offset:34816
	ds_read_b128 v[162:165], v234 offset:35840
	ds_read_b128 v[170:173], v234 offset:36864
	ds_read_b128 v[174:177], v234 offset:37888
	ds_read_b128 v[178:181], v234 offset:38912
	ds_read_b128 v[190:193], v234 offset:39936
	s_add_i32 s49, 0, 0x18000
	s_add_i32 s50, 0, 0x1c000
	s_add_u32 s18, s24, 0x160000
	s_addc_u32 s19, s25, 0
	s_mov_b32 m0, s33
	s_nop 0
	global_load_lds_dwordx4 v208, s[18:19]
	s_mov_b32 m0, s37
	s_nop 0
	global_load_lds_dwordx4 v206, s[18:19]
	s_waitcnt vmcnt(8)
	s_waitcnt lgkmcnt(0)
	v_mfma_f32_16x16x32_bf16 v[186:189], v[66:69], v[150:153], v[186:189]
	v_mfma_f32_16x16x32_bf16 v[186:189], v[78:81], v[154:157], v[186:189]
	s_barrier
	s_setprio 1
	v_mfma_f32_16x16x32_bf16 v[182:185], v[98:101], v[154:157], v[182:185]
	v_mfma_f32_16x16x32_bf16 v[182:185], v[86:89], v[150:153], v[182:185]
	v_mfma_f32_16x16x32_bf16 v[134:137], v[86:89], v[158:161], v[134:137]
	v_mfma_f32_16x16x32_bf16 v[134:137], v[98:101], v[162:165], v[134:137]
	v_mfma_f32_16x16x32_bf16 v[138:141], v[78:81], v[162:165], v[138:141]
	v_mfma_f32_16x16x32_bf16 v[138:141], v[66:69], v[158:161], v[138:141]
	v_mfma_f32_16x16x32_bf16 v[114:117], v[66:69], v[170:173], v[114:117]
	v_mfma_f32_16x16x32_bf16 v[114:117], v[78:81], v[174:177], v[114:117]
	v_mfma_f32_16x16x32_bf16 v[110:113], v[98:101], v[174:177], v[110:113]
	v_mfma_f32_16x16x32_bf16 v[110:113], v[86:89], v[170:173], v[110:113]
	v_mfma_f32_16x16x32_bf16 v[82:85], v[86:89], v[178:181], v[82:85]
	v_mfma_f32_16x16x32_bf16 v[82:85], v[98:101], v[190:193], v[82:85]
	v_mfma_f32_16x16x32_bf16 v[90:93], v[78:81], v[190:193], v[90:93]
	v_mfma_f32_16x16x32_bf16 v[90:93], v[66:69], v[178:181], v[90:93]
	v_mfma_f32_16x16x32_bf16 v[166:169], v[106:109], v[150:153], v[166:169]
	v_mfma_f32_16x16x32_bf16 v[166:169], v[118:121], v[154:157], v[166:169]
	v_mfma_f32_16x16x32_bf16 v[146:149], v[142:145], v[154:157], v[146:149]
	v_mfma_f32_16x16x32_bf16 v[146:149], v[130:133], v[150:153], v[146:149]
	v_mfma_f32_16x16x32_bf16 v[122:125], v[130:133], v[158:161], v[122:125]
	v_mfma_f32_16x16x32_bf16 v[122:125], v[142:145], v[162:165], v[122:125]
	v_mfma_f32_16x16x32_bf16 v[126:129], v[118:121], v[162:165], v[126:129]
	v_mfma_f32_16x16x32_bf16 v[126:129], v[106:109], v[158:161], v[126:129]
	v_mfma_f32_16x16x32_bf16 v[102:105], v[106:109], v[170:173], v[102:105]
	v_mfma_f32_16x16x32_bf16 v[102:105], v[118:121], v[174:177], v[102:105]
	v_mfma_f32_16x16x32_bf16 v[94:97], v[142:145], v[174:177], v[94:97]
	v_mfma_f32_16x16x32_bf16 v[94:97], v[130:133], v[170:173], v[94:97]
	v_mfma_f32_16x16x32_bf16 v[70:73], v[130:133], v[178:181], v[70:73]
	v_mfma_f32_16x16x32_bf16 v[70:73], v[142:145], v[190:193], v[70:73]
	v_mfma_f32_16x16x32_bf16 v[74:77], v[118:121], v[190:193], v[74:77]
	v_mfma_f32_16x16x32_bf16 v[74:77], v[106:109], v[178:181], v[74:77]
	s_setprio 0
	s_barrier
	ds_read_b128 v[150:153], v234 offset:49152
	ds_read_b128 v[154:157], v234 offset:50176
	ds_read_b128 v[158:161], v234 offset:51200
	ds_read_b128 v[162:165], v234 offset:52224
	ds_read_b128 v[170:173], v234 offset:53248
	ds_read_b128 v[174:177], v234 offset:54272
	ds_read_b128 v[178:181], v234 offset:55296
	ds_read_b128 v[190:193], v234 offset:56320
	s_add_i32 s18, s49, s26
	s_add_u32 vcc_lo, s22, s94
	s_addc_u32 vcc_hi, s23, s95
	s_mov_b32 m0, s18
	s_nop 0
	global_load_lds_dwordx4 v194, vcc
	s_add_i32 m0, s18, 0x2000
	s_add_u32 s18, s22, 0x160080
	s_addc_u32 s19, s23, 0
	s_add_i32 s22, s50, s26
	global_load_lds_dwordx4 v204, vcc
	s_mov_b32 m0, s22
	s_nop 0
	global_load_lds_dwordx4 v194, s[18:19]
	s_add_i32 m0, s22, 0x2000
	s_nop 0
	global_load_lds_dwordx4 v204, s[18:19]
	s_waitcnt vmcnt(6)
	s_waitcnt lgkmcnt(0)
	v_mfma_f32_16x16x32_bf16 v[62:65], v[66:69], v[150:153], v[62:65]
	v_mfma_f32_16x16x32_bf16 v[62:65], v[78:81], v[154:157], v[62:65]
	s_barrier
	s_setprio 1
	v_mfma_f32_16x16x32_bf16 v[58:61], v[98:101], v[154:157], v[58:61]
	v_mfma_f32_16x16x32_bf16 v[58:61], v[86:89], v[150:153], v[58:61]
	v_mfma_f32_16x16x32_bf16 v[42:45], v[86:89], v[158:161], v[42:45]
	v_mfma_f32_16x16x32_bf16 v[42:45], v[98:101], v[162:165], v[42:45]
	v_mfma_f32_16x16x32_bf16 v[46:49], v[78:81], v[162:165], v[46:49]
	v_mfma_f32_16x16x32_bf16 v[46:49], v[66:69], v[158:161], v[46:49]
	v_mfma_f32_16x16x32_bf16 v[30:33], v[66:69], v[170:173], v[30:33]
	v_mfma_f32_16x16x32_bf16 v[30:33], v[78:81], v[174:177], v[30:33]
	v_mfma_f32_16x16x32_bf16 v[26:29], v[98:101], v[174:177], v[26:29]
	v_mfma_f32_16x16x32_bf16 v[26:29], v[86:89], v[170:173], v[26:29]
	v_mfma_f32_16x16x32_bf16 v[10:13], v[86:89], v[178:181], v[10:13]
	v_mfma_f32_16x16x32_bf16 v[10:13], v[98:101], v[190:193], v[10:13]
	s_add_i32 s48, s48, 2
	v_mfma_f32_16x16x32_bf16 v[14:17], v[78:81], v[190:193], v[14:17]
	v_mfma_f32_16x16x32_bf16 v[14:17], v[66:69], v[178:181], v[14:17]
	s_add_u32 s46, s46, 0x100
	v_mfma_f32_16x16x32_bf16 v[54:57], v[106:109], v[150:153], v[54:57]
	v_mfma_f32_16x16x32_bf16 v[54:57], v[118:121], v[154:157], v[54:57]
	s_addc_u32 s47, s47, 0
	v_mfma_f32_16x16x32_bf16 v[50:53], v[142:145], v[154:157], v[50:53]
	v_mfma_f32_16x16x32_bf16 v[50:53], v[130:133], v[150:153], v[50:53]
	s_cmpk_gt_u32 s48, 0x55
	v_mfma_f32_16x16x32_bf16 v[34:37], v[130:133], v[158:161], v[34:37]
	v_mfma_f32_16x16x32_bf16 v[34:37], v[142:145], v[162:165], v[34:37]
	s_mov_b64 s[18:19], s[20:21]
	v_mfma_f32_16x16x32_bf16 v[38:41], v[118:121], v[162:165], v[38:41]
	v_mfma_f32_16x16x32_bf16 v[38:41], v[106:109], v[158:161], v[38:41]
	v_mfma_f32_16x16x32_bf16 v[22:25], v[106:109], v[170:173], v[22:25]
	v_mfma_f32_16x16x32_bf16 v[22:25], v[118:121], v[174:177], v[22:25]
	v_mfma_f32_16x16x32_bf16 v[18:21], v[142:145], v[174:177], v[18:21]
	v_mfma_f32_16x16x32_bf16 v[18:21], v[130:133], v[170:173], v[18:21]
	v_mfma_f32_16x16x32_bf16 v[2:5], v[130:133], v[178:181], v[2:5]
	v_mfma_f32_16x16x32_bf16 v[2:5], v[142:145], v[190:193], v[2:5]
	v_mfma_f32_16x16x32_bf16 v[6:9], v[118:121], v[190:193], v[6:9]
	v_mfma_f32_16x16x32_bf16 v[6:9], v[106:109], v[178:181], v[6:9]
	s_setprio 0
	s_barrier
	s_cbranch_scc1 .Lpeel_exit_8

.Lpeel_exit_8:
	s_add_u32 vcc_lo, s0, 0xffea0000
	s_addc_u32 vcc_hi, s1, -1
	s_mov_b32 m0, s38
	s_nop 0
	global_load_lds_dwordx4 v210, vcc
	s_mov_b32 m0, s40
	s_nop 0
	global_load_lds_dwordx4 v212, vcc
	s_add_i32 m0, s28, 0xc000
	s_nop 0
	global_load_lds_dwordx4 v210, s[0:1]
	s_add_i32 m0, s28, 0xe000
	s_nop 0
	global_load_lds_dwordx4 v212, s[0:1]
